# segment-head ordering (asm guide 6.4): next tile's four K ds_reads issued before the post-barrier PV-tail MFMA in the attention loop, on top of v40
# baseline (speedup 1.0000x reference)
; __device__ __forceinline__ void finishSM(f32x16& p0, f32x16& p1, float alpha, float& l_reg, bf16x8& pa0, bf16x8& pa1, bf16x8& pa2, bf16x8& pa3) {
;   for (int r = 0; r < 16; ++r) p1[r] = __builtin_amdgcn_exp2f(p1[r]);
;   float ps = 0; for (int r = 0; r < 16; ++r) ps += p0[r]; for (int r = 0; r < 16; ++r) ps += p1[r];
;   { auto rr = __builtin_amdgcn_permlane32_swap(__float_as_uint(ps), __float_as_uint(ps), false, false);
;     ps = __uint_as_float(rr[0]) + __uint_as_float(rr[1]); }
;   l_reg = l_reg * alpha + ps;
;     ...
;   PK4(p0, 0, pa0); PK4(p0, 8, pa1); PK4(p1, 0, pa2); PK4(p1, 8, pa3);
;     ...
; }
; __device__ __forceinline__ void qkt(f32x16& p0, f32x16& p1, const bf16* Ks, const bf16x8* qr, int r32, int hi) {
;   p0 = f32x16{}; p1 = f32x16{};
;   for (int d0 = 0; d0 < 8; ++d0) { int cb = (d0 * 16 + hi * 8) * 2;
;     bf16x8 b0 = *reinterpret_cast<const bf16x8*>((const char*)Ks + KSWZ(r32, cb));
;     bf16x8 b1 = *reinterpret_cast<const bf16x8*>((const char*)Ks + KSWZ(32 + r32, cb));
;     p0 = __builtin_amdgcn_mfma_f32_32x32x16_bf16(b0, qr[d0], p0, 0, 0, 0);
;     p1 = __builtin_amdgcn_mfma_f32_32x32x16_bf16(b1, qr[d0], p1, 0, 0, 0); }
; }
; __device__ __forceinline__ int v_st(int k, int c) { const int kk = (k & ~0xC) | ((k & 4) << 1) | ((k & 8) >> 1); return ((kk >> 3) * 4 + (c >> 5)) * 512 + ((kk & 7) * 32 + (c & 31)) * 2; }
; __device__ __forceinline__ int v_rd_base(int lane) { return ((lane & 3) << 3) | (((lane >> 2) & 3) << 6) | (((lane >> 4) & 1) << 5) | (((lane >> 5) & 1) << 8); }
; template <int OFF> __device__ __forceinline__ s16x4 tr_read(int vb) {
;   s16x4 r; asm volatile("ds_read_b64_tr_b16 %0, %1 offset:%2" : "=&v"(r) : "v"(vb), "i"(OFF) : "memory"); return r;
; }
; template <int D0> __device__ __forceinline__ void pv_one(f32x16& od, int vb, bf16x8 pa0, bf16x8 pa1, bf16x8 pa2, bf16x8 pa3) {
;   const s16x4 l0 = tr_read<v_rd_off(D0, 0, 0)>(vb), h0 = tr_read<v_rd_off(D0, 0, 1)>(vb), l1 = tr_read<v_rd_off(D0, 1, 0)>(vb), h1 = tr_read<v_rd_off(D0, 1, 1)>(vb);
;   const s16x4 l2 = tr_read<v_rd_off(D0, 2, 0)>(vb), h2 = tr_read<v_rd_off(D0, 2, 1)>(vb), l3 = tr_read<v_rd_off(D0, 3, 0)>(vb), h3 = tr_read<v_rd_off(D0, 3, 1)>(vb);
;   asm volatile("s_waitcnt lgkmcnt(0)" ::: "memory"); SBAR();
;     ...
;   od = __builtin_amdgcn_mfma_f32_32x32x16_bf16(pa0, PK(l0, h0), od, 0, 0, 0);
;   od = __builtin_amdgcn_mfma_f32_32x32x16_bf16(pa1, PK(l1, h1), od, 0, 0, 0);
.LBB0_352:
	s_waitcnt lgkmcnt(0)
	s_barrier
	ds_read_b128 v[80:83], v207 offset:16384
	ds_read_b128 v[84:87], v207 offset:24576
	ds_read_b128 v[162:165], v208 offset:16384
	ds_read_b128 v[166:169], v208 offset:24576
	v_exp_f32_e32 v170, v72
	v_exp_f32_e32 v171, v73
	v_exp_f32_e32 v172, v74
	v_exp_f32_e32 v173, v75
	v_exp_f32_e32 v174, v76
	v_exp_f32_e32 v175, v77
	v_exp_f32_e32 v176, v78
	v_exp_f32_e32 v79, v79
	s_waitcnt lgkmcnt(3)
	v_mfma_f32_32x32x16_bf16 v[96:111], v[80:83], v[142:145], 0
	v_exp_f32_e32 v236, v64
	v_add_f32_e32 v64, 0, v229
	v_add_f32_e32 v64, v243, v64
	v_add_f32_e32 v64, v244, v64
	s_waitcnt lgkmcnt(2)
	v_mfma_f32_32x32x16_bf16 v[80:95], v[84:87], v[142:145], 0
	v_add_f32_e32 v64, v246, v64
	v_add_f32_e32 v64, v242, v64
	v_add_f32_e32 v64, v245, v64
	s_waitcnt lgkmcnt(1)
	v_mfma_f32_32x32x16_bf16 v[96:111], v[162:165], v[138:141], v[96:111]
	v_add_f32_e32 v64, v227, v64
	v_add_f32_e32 v64, v228, v64
	v_add_f32_e32 v64, v223, v64
	s_waitcnt lgkmcnt(0)
	v_mfma_f32_32x32x16_bf16 v[80:95], v[166:169], v[138:141], v[80:95]
	ds_read_b128 v[162:165], v209 offset:16384
	ds_read_b128 v[166:169], v209 offset:24576
	v_add_f32_e32 v64, v226, v64
	v_add_f32_e32 v64, v224, v64
	v_add_f32_e32 v64, v225, v64
	v_add_f32_e32 v64, v220, v64
	v_exp_f32_e32 v237, v65
	s_waitcnt lgkmcnt(1)
	v_mfma_f32_32x32x16_bf16 v[96:111], v[162:165], v[112:115], v[96:111]
	v_add_f32_e32 v64, v222, v64
	v_exp_f32_e32 v238, v66
	v_add_f32_e32 v64, v219, v64
	v_exp_f32_e32 v239, v67
	s_waitcnt lgkmcnt(0)
	v_mfma_f32_32x32x16_bf16 v[80:95], v[166:169], v[112:115], v[80:95]
	ds_read_b128 v[162:165], v210 offset:16384
	ds_read_b128 v[166:169], v210 offset:24576
	v_add_f32_e32 v64, v221, v64
	v_exp_f32_e32 v247, v68
	v_add_f32_e32 v64, v236, v64
	v_exp_f32_e32 v248, v69
	s_waitcnt lgkmcnt(1)
	v_mfma_f32_32x32x16_bf16 v[96:111], v[162:165], v[116:119], v[96:111]
	v_add_f32_e32 v64, v237, v64
	v_exp_f32_e32 v249, v70
	v_add_f32_e32 v64, v238, v64
	v_exp_f32_e32 v252, v71
	s_waitcnt lgkmcnt(0)
	v_mfma_f32_32x32x16_bf16 v[80:95], v[166:169], v[116:119], v[80:95]
	ds_read_b128 v[162:165], v190 offset:16384
	ds_read_b128 v[166:169], v190 offset:24576
	v_add_f32_e32 v64, v239, v64
	v_add_f32_e32 v64, v247, v64
	v_add_f32_e32 v64, v248, v64
	v_add_f32_e32 v64, v249, v64
	v_add_f32_e32 v64, v252, v64
	v_add_f32_e32 v64, v170, v64
	s_waitcnt lgkmcnt(1)
	v_mfma_f32_32x32x16_bf16 v[96:111], v[162:165], v[120:123], v[96:111]
	v_add_f32_e32 v64, v171, v64
	v_add_f32_e32 v64, v172, v64
	v_add_f32_e32 v64, v173, v64
	v_add_f32_e32 v64, v174, v64
	v_add_f32_e32 v64, v175, v64
	s_waitcnt lgkmcnt(0)
	v_mfma_f32_32x32x16_bf16 v[80:95], v[166:169], v[120:123], v[80:95]
	ds_read_b128 v[162:165], v191 offset:16384
	ds_read_b128 v[166:169], v191 offset:24576
	v_add_f32_e32 v64, v176, v64
	v_add_f32_e32 v64, v79, v64
	v_mov_b32_e32 v65, v64
	s_nop 1
	v_permlane32_swap_b32_e32 v64, v65
	v_add_f32_e32 v64, v64, v65
	s_waitcnt lgkmcnt(1)
	v_mfma_f32_32x32x16_bf16 v[96:111], v[162:165], v[124:127], v[96:111]
	v_add_f32_e32 v128, v215, v64
	v_cvt_pk_bf16_f32 v64, v229, v243
	v_cvt_pk_bf16_f32 v65, v244, v246
	v_cvt_pk_bf16_f32 v66, v242, v245
	v_cvt_pk_bf16_f32 v67, v227, v228
	s_waitcnt lgkmcnt(0)
	v_mfma_f32_32x32x16_bf16 v[80:95], v[166:169], v[124:127], v[80:95]
	ds_read_b128 v[162:165], v192 offset:16384
	ds_read_b128 v[166:169], v192 offset:24576
	v_cvt_pk_bf16_f32 v68, v223, v226
	v_cvt_pk_bf16_f32 v69, v224, v225
	v_cvt_pk_bf16_f32 v70, v220, v222
	v_cvt_pk_bf16_f32 v71, v219, v221
	v_cvt_pk_bf16_f32 v72, v236, v237
	v_cvt_pk_bf16_f32 v73, v238, v239
	s_waitcnt lgkmcnt(1)
	v_mfma_f32_32x32x16_bf16 v[96:111], v[162:165], v[130:133], v[96:111]
	v_cvt_pk_bf16_f32 v74, v247, v248
	v_cvt_pk_bf16_f32 v75, v249, v252
	v_cvt_pk_bf16_f32 v76, v170, v171
	v_cvt_pk_bf16_f32 v77, v172, v173
	v_cvt_pk_bf16_f32 v78, v174, v175
	s_waitcnt lgkmcnt(0)
	v_mfma_f32_32x32x16_bf16 v[80:95], v[166:169], v[130:133], v[80:95]
	ds_read_b128 v[162:165], v193 offset:16384
	ds_read_b128 v[166:169], v193 offset:24576
	ds_read_b64_tr_b16 v[180:181], v206 offset:0
	ds_read_b64_tr_b16 v[182:183], v206 offset:0x800
	ds_read_b64_tr_b16 v[184:185], v206 offset:0x1000
	ds_read_b64_tr_b16 v[186:187], v206 offset:0x1800
	ds_read_b64_tr_b16 v[216:217], v206 offset:0x2000
	ds_read_b64_tr_b16 v[218:219], v206 offset:0x2800
	ds_read_b64_tr_b16 v[220:221], v206 offset:0x3000
	ds_read_b64_tr_b16 v[222:223], v206 offset:0x3800
	v_cvt_pk_bf16_f32 v79, v176, v79
	s_nop 0
	v_permlane32_swap_b32_e32 v64, v66
	v_permlane32_swap_b32_e32 v65, v67
	v_permlane32_swap_b32_e32 v68, v70
	v_permlane32_swap_b32_e32 v69, v71
	s_waitcnt lgkmcnt(9)
	v_mfma_f32_32x32x16_bf16 v[96:111], v[162:165], v[134:137], v[96:111]
	v_permlane32_swap_b32_e32 v72, v74
	v_permlane32_swap_b32_e32 v73, v75
	v_permlane32_swap_b32_e32 v76, v78
	v_permlane32_swap_b32_e32 v77, v79
	s_waitcnt lgkmcnt(8)
	v_mfma_f32_32x32x16_bf16 v[80:95], v[166:169], v[134:137], v[80:95]
	s_waitcnt vmcnt(0)
	ds_write_b128 v211, v[146:149] offset:32768
	s_waitcnt lgkmcnt(7)
	v_mfma_f32_32x32x16_bf16 v[0:15], v[64:67], v[180:183], v[0:15]
	ds_read_b64_tr_b16 v[180:181], v206 offset:0x200
	ds_read_b64_tr_b16 v[182:183], v206 offset:0xa00
	v_add_co_u32_e32 v166, vcc, s19, v178
	s_nop 1
	v_addc_co_u32_e32 v167, vcc, -1, v179, vcc
	v_add_co_u32_e32 v170, vcc, s20, v178
	s_nop 1
	v_addc_co_u32_e32 v171, vcc, -1, v179, vcc
	s_waitcnt lgkmcnt(7)
	v_mfma_f32_32x32x16_bf16 v[0:15], v[68:71], v[184:187], v[0:15]
	ds_read_b64_tr_b16 v[184:185], v206 offset:0x1200
	ds_read_b64_tr_b16 v[186:187], v206 offset:0x1a00
	global_load_dwordx4 v[162:165], v[166:167], off
	global_load_dwordx4 v[166:169], v[166:167], off offset:-512
	global_load_dwordx4 v[174:177], v[170:171], off
	global_load_dwordx4 v[170:173], v[170:171], off offset:-512
	s_waitcnt lgkmcnt(7)
; __device__ __forceinline__ void finishSM(f32x16& p0, f32x16& p1, float alpha, float& l_reg, bf16x8& pa0, bf16x8& pa1, bf16x8& pa2, bf16x8& pa3) {
;   for (int r = 0; r < 16; ++r) p1[r] = __builtin_amdgcn_exp2f(p1[r]);
;   float ps = 0; for (int r = 0; r < 16; ++r) ps += p0[r]; for (int r = 0; r < 16; ++r) ps += p1[r];
;   { auto rr = __builtin_amdgcn_permlane32_swap(__float_as_uint(ps), __float_as_uint(ps), false, false);
;     ps = __uint_as_float(rr[0]) + __uint_as_float(rr[1]); }
;   l_reg = l_reg * alpha + ps;
;     ...
;   PK4(p0, 0, pa0); PK4(p0, 8, pa1); PK4(p1, 0, pa2); PK4(p1, 8, pa3);
;     ...
; }
; __device__ __forceinline__ void qkt(f32x16& p0, f32x16& p1, const bf16* Ks, const bf16x8* qr, int r32, int hi) {
;   p0 = f32x16{}; p1 = f32x16{};
;   for (int d0 = 0; d0 < 8; ++d0) { int cb = (d0 * 16 + hi * 8) * 2;
;     bf16x8 b0 = *reinterpret_cast<const bf16x8*>((const char*)Ks + KSWZ(r32, cb));
;     bf16x8 b1 = *reinterpret_cast<const bf16x8*>((const char*)Ks + KSWZ(32 + r32, cb));
;     p0 = __builtin_amdgcn_mfma_f32_32x32x16_bf16(b0, qr[d0], p0, 0, 0, 0);
;     p1 = __builtin_amdgcn_mfma_f32_32x32x16_bf16(b1, qr[d0], p1, 0, 0, 0); }
; }
; __device__ __forceinline__ int v_st(int k, int c) { const int kk = (k & ~0xC) | ((k & 4) << 1) | ((k & 8) >> 1); return ((kk >> 3) * 4 + (c >> 5)) * 512 + ((kk & 7) * 32 + (c & 31)) * 2; }
; __device__ __forceinline__ int v_rd_base(int lane) { return ((lane & 3) << 3) | (((lane >> 2) & 3) << 6) | (((lane >> 4) & 1) << 5) | (((lane >> 5) & 1) << 8); }
; template <int OFF> __device__ __forceinline__ s16x4 tr_read(int vb) {
;   s16x4 r; asm volatile("ds_read_b64_tr_b16 %0, %1 offset:%2" : "=&v"(r) : "v"(vb), "i"(OFF) : "memory"); return r;
; }
; template <int D0> __device__ __forceinline__ void pv_one(f32x16& od, int vb, bf16x8 pa0, bf16x8 pa1, bf16x8 pa2, bf16x8 pa3) {
;   const s16x4 l0 = tr_read<v_rd_off(D0, 0, 0)>(vb), h0 = tr_read<v_rd_off(D0, 0, 1)>(vb), l1 = tr_read<v_rd_off(D0, 1, 0)>(vb), h1 = tr_read<v_rd_off(D0, 1, 1)>(vb);
;   const s16x4 l2 = tr_read<v_rd_off(D0, 2, 0)>(vb), h2 = tr_read<v_rd_off(D0, 2, 1)>(vb), l3 = tr_read<v_rd_off(D0, 3, 0)>(vb), h3 = tr_read<v_rd_off(D0, 3, 1)>(vb);
;   asm volatile("s_waitcnt lgkmcnt(0)" ::: "memory"); SBAR();
;     ...
;   od = __builtin_amdgcn_mfma_f32_32x32x16_bf16(pa0, PK(l0, h0), od, 0, 0, 0);
;   od = __builtin_amdgcn_mfma_f32_32x32x16_bf16(pa1, PK(l1, h1), od, 0, 0, 0);
	v_mfma_f32_32x32x16_bf16 v[0:15], v[72:75], v[216:219], v[0:15]
	ds_read_b64_tr_b16 v[216:217], v206 offset:0x2200
	ds_read_b64_tr_b16 v[218:219], v206 offset:0x2a00
	s_waitcnt lgkmcnt(7)
	v_mfma_f32_32x32x16_bf16 v[0:15], v[76:79], v[220:223], v[0:15]
	ds_read_b64_tr_b16 v[220:221], v206 offset:0x3200
	ds_read_b64_tr_b16 v[222:223], v206 offset:0x3a00
	ds_write_b128 v212, v[150:153] offset:32768
	s_waitcnt lgkmcnt(7)
	v_mfma_f32_32x32x16_bf16 v[16:31], v[64:67], v[180:183], v[16:31]
	ds_read_b64_tr_b16 v[180:181], v206 offset:0x400
	ds_read_b64_tr_b16 v[182:183], v206 offset:0xc00
	s_waitcnt lgkmcnt(7)
	v_mfma_f32_32x32x16_bf16 v[16:31], v[68:71], v[184:187], v[16:31]
	ds_read_b64_tr_b16 v[184:185], v206 offset:0x1400
	ds_read_b64_tr_b16 v[186:187], v206 offset:0x1c00
	s_waitcnt lgkmcnt(7)
	v_mfma_f32_32x32x16_bf16 v[16:31], v[72:75], v[216:219], v[16:31]
	ds_read_b64_tr_b16 v[216:217], v206 offset:0x2400
	ds_read_b64_tr_b16 v[218:219], v206 offset:0x2c00
	s_waitcnt lgkmcnt(7)
	v_mfma_f32_32x32x16_bf16 v[16:31], v[76:79], v[220:223], v[16:31]
	ds_read_b64_tr_b16 v[220:221], v206 offset:0x3400
	ds_read_b64_tr_b16 v[222:223], v206 offset:0x3c00
	ds_write_b128 v213, v[154:157] offset:32768
	s_waitcnt lgkmcnt(7)
	v_mfma_f32_32x32x16_bf16 v[32:47], v[64:67], v[180:183], v[32:47]
	ds_read_b64_tr_b16 v[180:181], v206 offset:0x600
	ds_read_b64_tr_b16 v[182:183], v206 offset:0xe00
	v_exp_f32_e32 v215, v108
	v_exp_f32_e32 v188, v102
	s_waitcnt lgkmcnt(7)
	v_mfma_f32_32x32x16_bf16 v[32:47], v[68:71], v[184:187], v[32:47]
	ds_read_b64_tr_b16 v[184:185], v206 offset:0x1600
	ds_read_b64_tr_b16 v[186:187], v206 offset:0x1e00
	v_exp_f32_e32 v189, v103
	v_exp_f32_e32 v196, v104
	s_waitcnt lgkmcnt(7)
	v_mfma_f32_32x32x16_bf16 v[32:47], v[72:75], v[216:219], v[32:47]
	ds_read_b64_tr_b16 v[216:217], v206 offset:0x2600
	ds_read_b64_tr_b16 v[218:219], v206 offset:0x2e00
	v_exp_f32_e32 v197, v105
	v_exp_f32_e32 v198, v106
	s_waitcnt lgkmcnt(7)
	v_mfma_f32_32x32x16_bf16 v[32:47], v[76:79], v[220:223], v[32:47]
	ds_read_b64_tr_b16 v[220:221], v206 offset:0x3600
	ds_read_b64_tr_b16 v[222:223], v206 offset:0x3e00
	v_exp_f32_e32 v199, v107
	ds_write_b128 v214, v[158:161] offset:32768
	s_waitcnt lgkmcnt(7)
	v_mfma_f32_32x32x16_bf16 v[48:63], v[64:67], v[180:183], v[48:63]
	v_exp_f32_e32 v181, v96
	v_exp_f32_e32 v183, v97
	s_waitcnt lgkmcnt(5)
	v_mfma_f32_32x32x16_bf16 v[48:63], v[68:71], v[184:187], v[48:63]
	v_exp_f32_e32 v184, v98
	v_exp_f32_e32 v185, v99
	v_exp_f32_e32 v186, v100
	v_exp_f32_e32 v187, v101
	s_waitcnt lgkmcnt(3)
	v_mfma_f32_32x32x16_bf16 v[48:63], v[72:75], v[216:219], v[48:63]
	v_exp_f32_e32 v216, v109
	v_exp_f32_e32 v217, v110
	v_exp_f32_e32 v218, v111
	s_waitcnt lgkmcnt(0)
	s_barrier
	ds_read_b128 v[64:67], v207 offset:32768
	ds_read_b128 v[96:99], v207 offset:40960
	ds_read_b128 v[146:149], v208 offset:32768
	ds_read_b128 v[150:153], v208 offset:40960
	v_mfma_f32_32x32x16_bf16 v[48:63], v[76:79], v[220:223], v[48:63]
	v_exp_f32_e32 v154, v88
	v_exp_f32_e32 v155, v89
	v_exp_f32_e32 v156, v90
	v_exp_f32_e32 v157, v91
	v_exp_f32_e32 v158, v92
	v_exp_f32_e32 v159, v93
	v_exp_f32_e32 v160, v94
	v_exp_f32_e32 v95, v95
	s_waitcnt lgkmcnt(3)
	v_mfma_f32_32x32x16_bf16 v[64:79], v[64:67], v[142:145], 0
	v_exp_f32_e32 v236, v80
	v_add_f32_e32 v80, 0, v181
	v_add_f32_e32 v80, v183, v80
	v_add_f32_e32 v80, v184, v80
	s_waitcnt lgkmcnt(2)
	v_mfma_f32_32x32x16_bf16 v[96:111], v[96:99], v[142:145], 0
	v_add_f32_e32 v80, v185, v80
	v_add_f32_e32 v80, v186, v80
	v_add_f32_e32 v80, v187, v80
	s_waitcnt lgkmcnt(1)
	v_mfma_f32_32x32x16_bf16 v[64:79], v[146:149], v[138:141], v[64:79]
	v_add_f32_e32 v80, v188, v80
	v_add_f32_e32 v80, v189, v80
	v_add_f32_e32 v80, v196, v80
	s_waitcnt lgkmcnt(0)
	v_mfma_f32_32x32x16_bf16 v[96:111], v[150:153], v[138:141], v[96:111]
	ds_read_b128 v[146:149], v209 offset:32768
	ds_read_b128 v[150:153], v209 offset:40960
	v_add_f32_e32 v80, v197, v80
	v_add_f32_e32 v80, v198, v80
	v_add_f32_e32 v80, v199, v80
	v_add_f32_e32 v80, v215, v80
	v_exp_f32_e32 v237, v81
	s_waitcnt lgkmcnt(1)
	v_mfma_f32_32x32x16_bf16 v[64:79], v[146:149], v[112:115], v[64:79]
	v_add_f32_e32 v80, v216, v80
	v_exp_f32_e32 v238, v82
	v_add_f32_e32 v80, v217, v80
	v_exp_f32_e32 v239, v83
	s_waitcnt lgkmcnt(0)
	v_mfma_f32_32x32x16_bf16 v[96:111], v[150:153], v[112:115], v[96:111]
	ds_read_b128 v[146:149], v210 offset:32768
	ds_read_b128 v[150:153], v210 offset:40960
	v_add_f32_e32 v80, v218, v80
	v_exp_f32_e32 v247, v84
	v_add_f32_e32 v80, v236, v80
	v_exp_f32_e32 v248, v85
	s_waitcnt lgkmcnt(1)
	v_mfma_f32_32x32x16_bf16 v[64:79], v[146:149], v[116:119], v[64:79]
	v_add_f32_e32 v80, v237, v80
	v_exp_f32_e32 v249, v86
	v_add_f32_e32 v80, v238, v80
	v_exp_f32_e32 v252, v87
	s_waitcnt lgkmcnt(0)
	v_mfma_f32_32x32x16_bf16 v[96:111], v[150:153], v[116:119], v[96:111]
	ds_read_b128 v[146:149], v190 offset:32768
	ds_read_b128 v[150:153], v190 offset:40960
	v_add_f32_e32 v80, v239, v80
	v_add_f32_e32 v80, v247, v80
	v_add_f32_e32 v80, v248, v80
	v_add_f32_e32 v80, v249, v80
	v_add_f32_e32 v80, v252, v80
	v_add_f32_e32 v80, v154, v80
	s_waitcnt lgkmcnt(1)
	v_mfma_f32_32x32x16_bf16 v[64:79], v[146:149], v[120:123], v[64:79]
	v_add_f32_e32 v80, v155, v80
	v_add_f32_e32 v80, v156, v80
	v_add_f32_e32 v80, v157, v80
	v_add_f32_e32 v80, v158, v80
	v_add_f32_e32 v80, v159, v80
	s_waitcnt lgkmcnt(0)
	v_mfma_f32_32x32x16_bf16 v[96:111], v[150:153], v[120:123], v[96:111]
	ds_read_b128 v[146:149], v191 offset:32768
	ds_read_b128 v[150:153], v191 offset:40960
	v_add_f32_e32 v80, v160, v80
	v_add_f32_e32 v180, v95, v80
	v_mov_b32_e32 v182, v180
	v_cvt_pk_bf16_f32 v80, v181, v183
	v_cvt_pk_bf16_f32 v81, v184, v185
	v_cvt_pk_bf16_f32 v82, v186, v187
	s_waitcnt lgkmcnt(1)
; __device__ __forceinline__ void finishSM(f32x16& p0, f32x16& p1, float alpha, float& l_reg, bf16x8& pa0, bf16x8& pa1, bf16x8& pa2, bf16x8& pa3) {
;   for (int r = 0; r < 16; ++r) p1[r] = __builtin_amdgcn_exp2f(p1[r]);
;   float ps = 0; for (int r = 0; r < 16; ++r) ps += p0[r]; for (int r = 0; r < 16; ++r) ps += p1[r];
;   { auto rr = __builtin_amdgcn_permlane32_swap(__float_as_uint(ps), __float_as_uint(ps), false, false);
;     ps = __uint_as_float(rr[0]) + __uint_as_float(rr[1]); }
;   l_reg = l_reg * alpha + ps;
;     ...
;   PK4(p0, 0, pa0); PK4(p0, 8, pa1); PK4(p1, 0, pa2); PK4(p1, 8, pa3);
;     ...
; }
; __device__ __forceinline__ void qkt(f32x16& p0, f32x16& p1, const bf16* Ks, const bf16x8* qr, int r32, int hi) {
;   p0 = f32x16{}; p1 = f32x16{};
;   for (int d0 = 0; d0 < 8; ++d0) { int cb = (d0 * 16 + hi * 8) * 2;
;     bf16x8 b0 = *reinterpret_cast<const bf16x8*>((const char*)Ks + KSWZ(r32, cb));
;     bf16x8 b1 = *reinterpret_cast<const bf16x8*>((const char*)Ks + KSWZ(32 + r32, cb));
;     p0 = __builtin_amdgcn_mfma_f32_32x32x16_bf16(b0, qr[d0], p0, 0, 0, 0);
;     p1 = __builtin_amdgcn_mfma_f32_32x32x16_bf16(b1, qr[d0], p1, 0, 0, 0); }
; }
; __device__ __forceinline__ int v_st(int k, int c) { const int kk = (k & ~0xC) | ((k & 4) << 1) | ((k & 8) >> 1); return ((kk >> 3) * 4 + (c >> 5)) * 512 + ((kk & 7) * 32 + (c & 31)) * 2; }
; __device__ __forceinline__ int v_rd_base(int lane) { return ((lane & 3) << 3) | (((lane >> 2) & 3) << 6) | (((lane >> 4) & 1) << 5) | (((lane >> 5) & 1) << 8); }
; template <int OFF> __device__ __forceinline__ s16x4 tr_read(int vb) {
;   s16x4 r; asm volatile("ds_read_b64_tr_b16 %0, %1 offset:%2" : "=&v"(r) : "v"(vb), "i"(OFF) : "memory"); return r;
; }
; template <int D0> __device__ __forceinline__ void pv_one(f32x16& od, int vb, bf16x8 pa0, bf16x8 pa1, bf16x8 pa2, bf16x8 pa3) {
;   const s16x4 l0 = tr_read<v_rd_off(D0, 0, 0)>(vb), h0 = tr_read<v_rd_off(D0, 0, 1)>(vb), l1 = tr_read<v_rd_off(D0, 1, 0)>(vb), h1 = tr_read<v_rd_off(D0, 1, 1)>(vb);
;   const s16x4 l2 = tr_read<v_rd_off(D0, 2, 0)>(vb), h2 = tr_read<v_rd_off(D0, 2, 1)>(vb), l3 = tr_read<v_rd_off(D0, 3, 0)>(vb), h3 = tr_read<v_rd_off(D0, 3, 1)>(vb);
;   asm volatile("s_waitcnt lgkmcnt(0)" ::: "memory"); SBAR();
;     ...
;   od = __builtin_amdgcn_mfma_f32_32x32x16_bf16(pa0, PK(l0, h0), od, 0, 0, 0);
;   od = __builtin_amdgcn_mfma_f32_32x32x16_bf16(pa1, PK(l1, h1), od, 0, 0, 0);
	v_mfma_f32_32x32x16_bf16 v[64:79], v[146:149], v[124:127], v[64:79]
	v_cvt_pk_bf16_f32 v83, v188, v189
	v_cvt_pk_bf16_f32 v84, v196, v197
	v_cvt_pk_bf16_f32 v85, v198, v199
	v_cvt_pk_bf16_f32 v86, v215, v216
	v_cvt_pk_bf16_f32 v87, v217, v218
	s_waitcnt lgkmcnt(0)
	v_mfma_f32_32x32x16_bf16 v[96:111], v[150:153], v[124:127], v[96:111]
	ds_read_b128 v[146:149], v192 offset:32768
	ds_read_b128 v[150:153], v192 offset:40960
	v_cvt_pk_bf16_f32 v88, v236, v237
	v_cvt_pk_bf16_f32 v89, v238, v239
	v_cvt_pk_bf16_f32 v90, v247, v248
	v_cvt_pk_bf16_f32 v91, v249, v252
	v_cvt_pk_bf16_f32 v92, v154, v155
	v_cvt_pk_bf16_f32 v93, v156, v157
	s_waitcnt lgkmcnt(1)
	v_mfma_f32_32x32x16_bf16 v[64:79], v[146:149], v[130:133], v[64:79]
	v_cvt_pk_bf16_f32 v94, v158, v159
	v_cvt_pk_bf16_f32 v95, v160, v95
	s_nop 1
	v_permlane32_swap_b32_e32 v180, v182
	v_permlane32_swap_b32_e32 v80, v82
	s_waitcnt lgkmcnt(0)
	v_mfma_f32_32x32x16_bf16 v[96:111], v[150:153], v[130:133], v[96:111]
	ds_read_b128 v[146:149], v193 offset:32768
	ds_read_b128 v[150:153], v193 offset:40960
	ds_read_b64_tr_b16 v[184:185], v206 offset:0x4000
	ds_read_b64_tr_b16 v[186:187], v206 offset:0x4800
	ds_read_b64_tr_b16 v[216:217], v206 offset:0x5000
	ds_read_b64_tr_b16 v[218:219], v206 offset:0x5800
	ds_read_b64_tr_b16 v[220:221], v206 offset:0x6000
	ds_read_b64_tr_b16 v[222:223], v206 offset:0x6800
	ds_read_b64_tr_b16 v[224:225], v206 offset:0x7000
	ds_read_b64_tr_b16 v[226:227], v206 offset:0x7800
	v_permlane32_swap_b32_e32 v81, v83
	v_permlane32_swap_b32_e32 v84, v86
	v_permlane32_swap_b32_e32 v85, v87
	v_permlane32_swap_b32_e32 v88, v90
	v_permlane32_swap_b32_e32 v89, v91
	v_permlane32_swap_b32_e32 v92, v94
	s_waitcnt lgkmcnt(9)
	v_mfma_f32_32x32x16_bf16 v[64:79], v[146:149], v[134:137], v[64:79]
	v_permlane32_swap_b32_e32 v93, v95
	s_waitcnt lgkmcnt(8)
	v_mfma_f32_32x32x16_bf16 v[96:111], v[150:153], v[134:137], v[96:111]
	s_waitcnt vmcnt(0)
	ds_write_b128 v211, v[162:165]
	s_waitcnt lgkmcnt(7)
	v_mfma_f32_32x32x16_bf16 v[0:15], v[80:83], v[184:187], v[0:15]
	ds_read_b64_tr_b16 v[184:185], v206 offset:0x4200
	ds_read_b64_tr_b16 v[186:187], v206 offset:0x4a00
	v_add_co_u32_e32 v150, vcc, s21, v178
	s_nop 1
	v_addc_co_u32_e32 v151, vcc, -1, v179, vcc
	v_add_co_u32_e32 v154, vcc, s22, v178
	s_nop 1
	v_addc_co_u32_e32 v155, vcc, -1, v179, vcc
	s_waitcnt lgkmcnt(7)
	v_mfma_f32_32x32x16_bf16 v[0:15], v[84:87], v[216:219], v[0:15]
	ds_read_b64_tr_b16 v[216:217], v206 offset:0x5200
	ds_read_b64_tr_b16 v[218:219], v206 offset:0x5a00
	global_load_dwordx4 v[146:149], v[150:151], off
	global_load_dwordx4 v[150:153], v[150:151], off offset:-512
	global_load_dwordx4 v[158:161], v[154:155], off
	global_load_dwordx4 v[154:157], v[154:155], off offset:-512
	s_waitcnt lgkmcnt(7)
	v_mfma_f32_32x32x16_bf16 v[0:15], v[88:91], v[220:223], v[0:15]
	ds_read_b64_tr_b16 v[220:221], v206 offset:0x6200
	ds_read_b64_tr_b16 v[222:223], v206 offset:0x6a00
	s_waitcnt lgkmcnt(7)
	v_mfma_f32_32x32x16_bf16 v[0:15], v[92:95], v[224:227], v[0:15]
	ds_read_b64_tr_b16 v[224:225], v206 offset:0x7200
	ds_read_b64_tr_b16 v[226:227], v206 offset:0x7a00
	ds_write_b128 v212, v[174:177]
	s_waitcnt lgkmcnt(7)
	v_mfma_f32_32x32x16_bf16 v[16:31], v[80:83], v[184:187], v[16:31]
	ds_read_b64_tr_b16 v[184:185], v206 offset:0x4400
	ds_read_b64_tr_b16 v[186:187], v206 offset:0x4c00
	s_waitcnt lgkmcnt(7)
	v_mfma_f32_32x32x16_bf16 v[16:31], v[84:87], v[216:219], v[16:31]
	ds_read_b64_tr_b16 v[216:217], v206 offset:0x5400
	ds_read_b64_tr_b16 v[218:219], v206 offset:0x5c00
	s_waitcnt lgkmcnt(7)
	v_mfma_f32_32x32x16_bf16 v[16:31], v[88:91], v[220:223], v[16:31]
	ds_read_b64_tr_b16 v[220:221], v206 offset:0x6400
	ds_read_b64_tr_b16 v[222:223], v206 offset:0x6c00
	s_waitcnt lgkmcnt(7)
	v_mfma_f32_32x32x16_bf16 v[16:31], v[92:95], v[224:227], v[16:31]
	ds_read_b64_tr_b16 v[224:225], v206 offset:0x7400
	ds_read_b64_tr_b16 v[226:227], v206 offset:0x7c00
	ds_write_b128 v213, v[166:169]
	s_waitcnt lgkmcnt(7)
	v_mfma_f32_32x32x16_bf16 v[32:47], v[80:83], v[184:187], v[32:47]
	ds_read_b64_tr_b16 v[184:185], v206 offset:0x4600
	ds_read_b64_tr_b16 v[186:187], v206 offset:0x4e00
	v_exp_f32_e32 v215, v74
	v_exp_f32_e32 v188, v68
	s_waitcnt lgkmcnt(7)
	v_mfma_f32_32x32x16_bf16 v[32:47], v[84:87], v[216:219], v[32:47]
	ds_read_b64_tr_b16 v[216:217], v206 offset:0x5600
	ds_read_b64_tr_b16 v[218:219], v206 offset:0x5e00
	v_exp_f32_e32 v189, v69
	v_exp_f32_e32 v196, v70
	s_waitcnt lgkmcnt(7)
	v_mfma_f32_32x32x16_bf16 v[32:47], v[88:91], v[220:223], v[32:47]
	ds_read_b64_tr_b16 v[220:221], v206 offset:0x6600
	ds_read_b64_tr_b16 v[222:223], v206 offset:0x6e00
	v_exp_f32_e32 v197, v71
	v_exp_f32_e32 v198, v72
	s_waitcnt lgkmcnt(7)
	v_mfma_f32_32x32x16_bf16 v[32:47], v[92:95], v[224:227], v[32:47]
	ds_read_b64_tr_b16 v[224:225], v206 offset:0x7600
	ds_read_b64_tr_b16 v[226:227], v206 offset:0x7e00
	v_exp_f32_e32 v199, v73
	ds_write_b128 v214, v[170:173]
	s_waitcnt lgkmcnt(7)
	v_mfma_f32_32x32x16_bf16 v[48:63], v[80:83], v[184:187], v[48:63]
	v_exp_f32_e32 v184, v64
	v_exp_f32_e32 v185, v65
	v_exp_f32_e32 v186, v66
	v_exp_f32_e32 v187, v67
	s_waitcnt lgkmcnt(5)
	v_mfma_f32_32x32x16_bf16 v[48:63], v[84:87], v[216:219], v[48:63]
	v_exp_f32_e32 v219, v78
	v_exp_f32_e32 v216, v75
	s_waitcnt lgkmcnt(3)
	v_mfma_f32_32x32x16_bf16 v[48:63], v[88:91], v[220:223], v[48:63]
	v_exp_f32_e32 v220, v79
	v_exp_f32_e32 v217, v76
	v_exp_f32_e32 v218, v77
	s_waitcnt lgkmcnt(0)
	s_barrier
; __device__ __forceinline__ void finishSM(f32x16& p0, f32x16& p1, float alpha, float& l_reg, bf16x8& pa0, bf16x8& pa1, bf16x8& pa2, bf16x8& pa3) {
;   for (int r = 0; r < 16; ++r) p1[r] = __builtin_amdgcn_exp2f(p1[r]);
;   float ps = 0; for (int r = 0; r < 16; ++r) ps += p0[r]; for (int r = 0; r < 16; ++r) ps += p1[r];
;   { auto rr = __builtin_amdgcn_permlane32_swap(__float_as_uint(ps), __float_as_uint(ps), false, false);
;     ps = __uint_as_float(rr[0]) + __uint_as_float(rr[1]); }
;   l_reg = l_reg * alpha + ps;
;     ...
;   PK4(p0, 0, pa0); PK4(p0, 8, pa1); PK4(p1, 0, pa2); PK4(p1, 8, pa3);
;     ...
; }
; __device__ __forceinline__ void qkt(f32x16& p0, f32x16& p1, const bf16* Ks, const bf16x8* qr, int r32, int hi) {
;   p0 = f32x16{}; p1 = f32x16{};
;   for (int d0 = 0; d0 < 8; ++d0) { int cb = (d0 * 16 + hi * 8) * 2;
;     bf16x8 b0 = *reinterpret_cast<const bf16x8*>((const char*)Ks + KSWZ(r32, cb));
;     bf16x8 b1 = *reinterpret_cast<const bf16x8*>((const char*)Ks + KSWZ(32 + r32, cb));
;     p0 = __builtin_amdgcn_mfma_f32_32x32x16_bf16(b0, qr[d0], p0, 0, 0, 0);
;     p1 = __builtin_amdgcn_mfma_f32_32x32x16_bf16(b1, qr[d0], p1, 0, 0, 0); }
; }
; __device__ __forceinline__ int v_st(int k, int c) { const int kk = (k & ~0xC) | ((k & 4) << 1) | ((k & 8) >> 1); return ((kk >> 3) * 4 + (c >> 5)) * 512 + ((kk & 7) * 32 + (c & 31)) * 2; }
; __device__ __forceinline__ int v_rd_base(int lane) { return ((lane & 3) << 3) | (((lane >> 2) & 3) << 6) | (((lane >> 4) & 1) << 5) | (((lane >> 5) & 1) << 8); }
; template <int OFF> __device__ __forceinline__ s16x4 tr_read(int vb) {
;   s16x4 r; asm volatile("ds_read_b64_tr_b16 %0, %1 offset:%2" : "=&v"(r) : "v"(vb), "i"(OFF) : "memory"); return r;
; }
; template <int D0> __device__ __forceinline__ void pv_one(f32x16& od, int vb, bf16x8 pa0, bf16x8 pa1, bf16x8 pa2, bf16x8 pa3) {
;   const s16x4 l0 = tr_read<v_rd_off(D0, 0, 0)>(vb), h0 = tr_read<v_rd_off(D0, 0, 1)>(vb), l1 = tr_read<v_rd_off(D0, 1, 0)>(vb), h1 = tr_read<v_rd_off(D0, 1, 1)>(vb);
;   const s16x4 l2 = tr_read<v_rd_off(D0, 2, 0)>(vb), h2 = tr_read<v_rd_off(D0, 2, 1)>(vb), l3 = tr_read<v_rd_off(D0, 3, 0)>(vb), h3 = tr_read<v_rd_off(D0, 3, 1)>(vb);
;   asm volatile("s_waitcnt lgkmcnt(0)" ::: "memory"); SBAR();
;     ...
;   od = __builtin_amdgcn_mfma_f32_32x32x16_bf16(pa0, PK(l0, h0), od, 0, 0, 0);
;   od = __builtin_amdgcn_mfma_f32_32x32x16_bf16(pa1, PK(l1, h1), od, 0, 0, 0);
	ds_read_b128 v[64:67], v207
	ds_read_b128 v[68:71], v207 offset:8192
	ds_read_b128 v[162:165], v208
	ds_read_b128 v[166:169], v208 offset:8192
	v_mfma_f32_32x32x16_bf16 v[48:63], v[92:95], v[224:227], v[48:63]
	v_exp_f32_e32 v170, v104
	v_exp_f32_e32 v171, v105
	v_exp_f32_e32 v172, v106
	v_exp_f32_e32 v173, v107
	v_exp_f32_e32 v174, v108
	v_exp_f32_e32 v175, v109
	v_exp_f32_e32 v176, v110
	v_exp_f32_e32 v111, v111
	s_waitcnt lgkmcnt(3)
	v_mfma_f32_32x32x16_bf16 v[80:95], v[64:67], v[142:145], 0
	v_exp_f32_e32 v236, v96
	v_add_f32_e32 v96, 0, v184
	v_add_f32_e32 v96, v185, v96
	v_add_f32_e32 v96, v186, v96
	s_waitcnt lgkmcnt(2)
	v_mfma_f32_32x32x16_bf16 v[64:79], v[68:71], v[142:145], 0
	v_add_f32_e32 v96, v187, v96
	v_add_f32_e32 v96, v188, v96
	v_add_f32_e32 v96, v189, v96
	s_waitcnt lgkmcnt(1)
	v_mfma_f32_32x32x16_bf16 v[80:95], v[162:165], v[138:141], v[80:95]
	v_add_f32_e32 v96, v196, v96
	v_add_f32_e32 v96, v197, v96
	v_add_f32_e32 v96, v198, v96
	s_waitcnt lgkmcnt(0)
	v_mfma_f32_32x32x16_bf16 v[64:79], v[166:169], v[138:141], v[64:79]
	ds_read_b128 v[162:165], v209
	ds_read_b128 v[166:169], v209 offset:8192
	v_add_f32_e32 v96, v199, v96
	v_add_f32_e32 v96, v215, v96
	v_add_f32_e32 v96, v216, v96
	v_add_f32_e32 v96, v217, v96
	v_exp_f32_e32 v237, v97
	s_waitcnt lgkmcnt(1)
	v_mfma_f32_32x32x16_bf16 v[80:95], v[162:165], v[112:115], v[80:95]
	v_add_f32_e32 v96, v218, v96
	v_exp_f32_e32 v238, v98
	v_add_f32_e32 v96, v219, v96
	v_exp_f32_e32 v239, v99
	s_waitcnt lgkmcnt(0)
	v_mfma_f32_32x32x16_bf16 v[64:79], v[166:169], v[112:115], v[64:79]
	ds_read_b128 v[162:165], v210
	ds_read_b128 v[166:169], v210 offset:8192
	v_add_f32_e32 v96, v220, v96
	v_exp_f32_e32 v247, v100
	v_add_f32_e32 v96, v236, v96
	v_exp_f32_e32 v248, v101
	s_waitcnt lgkmcnt(1)
	v_mfma_f32_32x32x16_bf16 v[80:95], v[162:165], v[116:119], v[80:95]
	v_add_f32_e32 v96, v237, v96
	v_exp_f32_e32 v249, v102
	v_add_f32_e32 v96, v238, v96
	v_exp_f32_e32 v252, v103
	s_waitcnt lgkmcnt(0)
	v_mfma_f32_32x32x16_bf16 v[64:79], v[166:169], v[116:119], v[64:79]
	ds_read_b128 v[162:165], v190 offset:0
	ds_read_b128 v[166:169], v190 offset:8192
	v_add_f32_e32 v96, v239, v96
	v_add_f32_e32 v96, v247, v96
	v_add_f32_e32 v96, v248, v96
	v_add_f32_e32 v96, v249, v96
	v_add_f32_e32 v96, v252, v96
	v_add_f32_e32 v96, v170, v96
	s_waitcnt lgkmcnt(1)
	v_mfma_f32_32x32x16_bf16 v[80:95], v[162:165], v[120:123], v[80:95]
	v_add_f32_e32 v96, v171, v96
	v_add_f32_e32 v96, v172, v96
	v_add_f32_e32 v96, v173, v96
	v_add_f32_e32 v96, v174, v96
	v_add_f32_e32 v96, v175, v96
	s_waitcnt lgkmcnt(0)
	v_mfma_f32_32x32x16_bf16 v[64:79], v[166:169], v[120:123], v[64:79]
	ds_read_b128 v[162:165], v191 offset:0
	ds_read_b128 v[166:169], v191 offset:8192
	v_add_f32_e32 v96, v176, v96
	v_add_f32_e32 v181, v111, v96
	v_mov_b32_e32 v183, v181
	s_nop 1
	v_permlane32_swap_b32_e32 v181, v183
	v_pk_add_f32 v[96:97], v[180:181], v[182:183]
	s_waitcnt lgkmcnt(1)
	v_mfma_f32_32x32x16_bf16 v[80:95], v[162:165], v[124:127], v[80:95]
	s_nop 0
	v_add_f32_e32 v96, v128, v96
	v_add_f32_e32 v128, v96, v97
	v_cvt_pk_bf16_f32 v96, v184, v185
	v_cvt_pk_bf16_f32 v97, v186, v187
	s_waitcnt lgkmcnt(0)
	v_mfma_f32_32x32x16_bf16 v[64:79], v[166:169], v[124:127], v[64:79]
	ds_read_b128 v[162:165], v192 offset:0
	ds_read_b128 v[166:169], v192 offset:8192
	v_cvt_pk_bf16_f32 v98, v188, v189
	v_cvt_pk_bf16_f32 v99, v196, v197
	v_cvt_pk_bf16_f32 v100, v198, v199
	v_cvt_pk_bf16_f32 v101, v215, v216
	v_cvt_pk_bf16_f32 v102, v217, v218
	v_cvt_pk_bf16_f32 v103, v219, v220
	s_waitcnt lgkmcnt(1)
	v_mfma_f32_32x32x16_bf16 v[80:95], v[162:165], v[130:133], v[80:95]
	v_cvt_pk_bf16_f32 v104, v236, v237
	v_cvt_pk_bf16_f32 v105, v238, v239
	v_cvt_pk_bf16_f32 v106, v247, v248
	v_cvt_pk_bf16_f32 v107, v249, v252
	v_cvt_pk_bf16_f32 v108, v170, v171
	s_waitcnt lgkmcnt(0)
	v_mfma_f32_32x32x16_bf16 v[64:79], v[166:169], v[130:133], v[64:79]
	ds_read_b128 v[162:165], v193 offset:0
	ds_read_b128 v[166:169], v193 offset:8192
	ds_read_b64_tr_b16 v[180:181], v206 offset:0x8000
	ds_read_b64_tr_b16 v[182:183], v206 offset:0x8800
	ds_read_b64_tr_b16 v[184:185], v206 offset:0x9000
	ds_read_b64_tr_b16 v[186:187], v206 offset:0x9800
	ds_read_b64_tr_b16 v[216:217], v206 offset:0xa000
	ds_read_b64_tr_b16 v[218:219], v206 offset:0xa800
	ds_read_b64_tr_b16 v[220:221], v206 offset:0xb000
	ds_read_b64_tr_b16 v[222:223], v206 offset:0xb800
	v_cvt_pk_bf16_f32 v109, v172, v173
	v_cvt_pk_bf16_f32 v110, v174, v175
	v_cvt_pk_bf16_f32 v111, v176, v111
	s_nop 0
	v_permlane32_swap_b32_e32 v96, v98
	v_permlane32_swap_b32_e32 v97, v99
	s_waitcnt lgkmcnt(9)
	v_mfma_f32_32x32x16_bf16 v[80:95], v[162:165], v[134:137], v[80:95]
	v_permlane32_swap_b32_e32 v100, v102
	v_permlane32_swap_b32_e32 v101, v103
	v_permlane32_swap_b32_e32 v104, v106
	v_permlane32_swap_b32_e32 v105, v107
	v_permlane32_swap_b32_e32 v108, v110
	s_waitcnt lgkmcnt(8)
	v_mfma_f32_32x32x16_bf16 v[64:79], v[166:169], v[134:137], v[64:79]
	v_permlane32_swap_b32_e32 v109, v111
	s_waitcnt vmcnt(0)
	ds_write_b128 v211, v[146:149] offset:16384
	s_waitcnt lgkmcnt(7)
	v_mfma_f32_32x32x16_bf16 v[0:15], v[96:99], v[180:183], v[0:15]
	ds_read_b64_tr_b16 v[180:181], v206 offset:0x8200
	ds_read_b64_tr_b16 v[182:183], v206 offset:0x8a00
	v_add_co_u32_e32 v166, vcc, s23, v178
	s_nop 1
	v_addc_co_u32_e32 v167, vcc, -1, v179, vcc
	v_add_co_u32_e32 v170, vcc, s24, v178
	s_nop 1
	v_addc_co_u32_e32 v171, vcc, -1, v179, vcc
	s_waitcnt lgkmcnt(7)
; __device__ __forceinline__ void finishSM(f32x16& p0, f32x16& p1, float alpha, float& l_reg, bf16x8& pa0, bf16x8& pa1, bf16x8& pa2, bf16x8& pa3) {
;   for (int r = 0; r < 16; ++r) p1[r] = __builtin_amdgcn_exp2f(p1[r]);
;   float ps = 0; for (int r = 0; r < 16; ++r) ps += p0[r]; for (int r = 0; r < 16; ++r) ps += p1[r];
;   { auto rr = __builtin_amdgcn_permlane32_swap(__float_as_uint(ps), __float_as_uint(ps), false, false);
;     ps = __uint_as_float(rr[0]) + __uint_as_float(rr[1]); }
;   l_reg = l_reg * alpha + ps;
;     ...
;   PK4(p0, 0, pa0); PK4(p0, 8, pa1); PK4(p1, 0, pa2); PK4(p1, 8, pa3);
;     ...
; }
; __device__ __forceinline__ void qkt(f32x16& p0, f32x16& p1, const bf16* Ks, const bf16x8* qr, int r32, int hi) {
;   p0 = f32x16{}; p1 = f32x16{};
;   for (int d0 = 0; d0 < 8; ++d0) { int cb = (d0 * 16 + hi * 8) * 2;
;     bf16x8 b0 = *reinterpret_cast<const bf16x8*>((const char*)Ks + KSWZ(r32, cb));
;     bf16x8 b1 = *reinterpret_cast<const bf16x8*>((const char*)Ks + KSWZ(32 + r32, cb));
;     p0 = __builtin_amdgcn_mfma_f32_32x32x16_bf16(b0, qr[d0], p0, 0, 0, 0);
;     p1 = __builtin_amdgcn_mfma_f32_32x32x16_bf16(b1, qr[d0], p1, 0, 0, 0); }
; }
; __device__ __forceinline__ int v_st(int k, int c) { const int kk = (k & ~0xC) | ((k & 4) << 1) | ((k & 8) >> 1); return ((kk >> 3) * 4 + (c >> 5)) * 512 + ((kk & 7) * 32 + (c & 31)) * 2; }
; __device__ __forceinline__ int v_rd_base(int lane) { return ((lane & 3) << 3) | (((lane >> 2) & 3) << 6) | (((lane >> 4) & 1) << 5) | (((lane >> 5) & 1) << 8); }
; template <int OFF> __device__ __forceinline__ s16x4 tr_read(int vb) {
;   s16x4 r; asm volatile("ds_read_b64_tr_b16 %0, %1 offset:%2" : "=&v"(r) : "v"(vb), "i"(OFF) : "memory"); return r;
; }
; template <int D0> __device__ __forceinline__ void pv_one(f32x16& od, int vb, bf16x8 pa0, bf16x8 pa1, bf16x8 pa2, bf16x8 pa3) {
;   const s16x4 l0 = tr_read<v_rd_off(D0, 0, 0)>(vb), h0 = tr_read<v_rd_off(D0, 0, 1)>(vb), l1 = tr_read<v_rd_off(D0, 1, 0)>(vb), h1 = tr_read<v_rd_off(D0, 1, 1)>(vb);
;   const s16x4 l2 = tr_read<v_rd_off(D0, 2, 0)>(vb), h2 = tr_read<v_rd_off(D0, 2, 1)>(vb), l3 = tr_read<v_rd_off(D0, 3, 0)>(vb), h3 = tr_read<v_rd_off(D0, 3, 1)>(vb);
;   asm volatile("s_waitcnt lgkmcnt(0)" ::: "memory"); SBAR();
;     ...
;   od = __builtin_amdgcn_mfma_f32_32x32x16_bf16(pa0, PK(l0, h0), od, 0, 0, 0);
;   od = __builtin_amdgcn_mfma_f32_32x32x16_bf16(pa1, PK(l1, h1), od, 0, 0, 0);
	v_mfma_f32_32x32x16_bf16 v[0:15], v[100:103], v[184:187], v[0:15]
	ds_read_b64_tr_b16 v[184:185], v206 offset:0x9200
	ds_read_b64_tr_b16 v[186:187], v206 offset:0x9a00
	global_load_dwordx4 v[162:165], v[166:167], off
	global_load_dwordx4 v[166:169], v[166:167], off offset:-512
	global_load_dwordx4 v[174:177], v[170:171], off
	global_load_dwordx4 v[170:173], v[170:171], off offset:-512
	s_waitcnt lgkmcnt(7)
	v_mfma_f32_32x32x16_bf16 v[0:15], v[104:107], v[216:219], v[0:15]
	ds_read_b64_tr_b16 v[216:217], v206 offset:0xa200
	ds_read_b64_tr_b16 v[218:219], v206 offset:0xaa00
	s_waitcnt lgkmcnt(7)
	v_mfma_f32_32x32x16_bf16 v[0:15], v[108:111], v[220:223], v[0:15]
	ds_read_b64_tr_b16 v[220:221], v206 offset:0xb200
	ds_read_b64_tr_b16 v[222:223], v206 offset:0xba00
	ds_write_b128 v212, v[158:161] offset:16384
	s_waitcnt lgkmcnt(7)
	v_mfma_f32_32x32x16_bf16 v[16:31], v[96:99], v[180:183], v[16:31]
	ds_read_b64_tr_b16 v[180:181], v206 offset:0x8400
	ds_read_b64_tr_b16 v[182:183], v206 offset:0x8c00
	s_waitcnt lgkmcnt(7)
	v_mfma_f32_32x32x16_bf16 v[16:31], v[100:103], v[184:187], v[16:31]
	ds_read_b64_tr_b16 v[184:185], v206 offset:0x9400
	ds_read_b64_tr_b16 v[186:187], v206 offset:0x9c00
	s_waitcnt lgkmcnt(7)
	v_mfma_f32_32x32x16_bf16 v[16:31], v[104:107], v[216:219], v[16:31]
	ds_read_b64_tr_b16 v[216:217], v206 offset:0xa400
	ds_read_b64_tr_b16 v[218:219], v206 offset:0xac00
	s_waitcnt lgkmcnt(7)
	v_mfma_f32_32x32x16_bf16 v[16:31], v[108:111], v[220:223], v[16:31]
	ds_read_b64_tr_b16 v[220:221], v206 offset:0xb400
	ds_read_b64_tr_b16 v[222:223], v206 offset:0xbc00
	ds_write_b128 v213, v[150:153] offset:16384
	s_waitcnt lgkmcnt(7)
	v_mfma_f32_32x32x16_bf16 v[32:47], v[96:99], v[180:183], v[32:47]
	ds_read_b64_tr_b16 v[180:181], v206 offset:0x8600
	ds_read_b64_tr_b16 v[182:183], v206 offset:0x8e00
	v_exp_f32_e32 v215, v92
	v_exp_f32_e32 v188, v86
	s_waitcnt lgkmcnt(7)
	v_mfma_f32_32x32x16_bf16 v[32:47], v[100:103], v[184:187], v[32:47]
	ds_read_b64_tr_b16 v[184:185], v206 offset:0x9600
	ds_read_b64_tr_b16 v[186:187], v206 offset:0x9e00
	v_exp_f32_e32 v189, v87
	v_exp_f32_e32 v196, v88
	s_waitcnt lgkmcnt(7)
	v_mfma_f32_32x32x16_bf16 v[32:47], v[104:107], v[216:219], v[32:47]
	ds_read_b64_tr_b16 v[216:217], v206 offset:0xa600
	ds_read_b64_tr_b16 v[218:219], v206 offset:0xae00
	v_exp_f32_e32 v197, v89
	v_exp_f32_e32 v198, v90
	s_waitcnt lgkmcnt(7)
	v_mfma_f32_32x32x16_bf16 v[32:47], v[108:111], v[220:223], v[32:47]
	ds_read_b64_tr_b16 v[220:221], v206 offset:0xb600
	ds_read_b64_tr_b16 v[222:223], v206 offset:0xbe00
	v_exp_f32_e32 v199, v91
	ds_write_b128 v214, v[154:157] offset:16384
	s_waitcnt lgkmcnt(7)
	v_mfma_f32_32x32x16_bf16 v[48:63], v[96:99], v[180:183], v[48:63]
	v_exp_f32_e32 v181, v80
	v_exp_f32_e32 v183, v81
	s_waitcnt lgkmcnt(5)
	v_mfma_f32_32x32x16_bf16 v[48:63], v[100:103], v[184:187], v[48:63]
	v_exp_f32_e32 v184, v82
	v_exp_f32_e32 v185, v83
	v_exp_f32_e32 v186, v84
	v_exp_f32_e32 v187, v85
	s_waitcnt lgkmcnt(3)
	v_mfma_f32_32x32x16_bf16 v[48:63], v[104:107], v[216:219], v[48:63]
	v_exp_f32_e32 v216, v93
	v_exp_f32_e32 v217, v94
	v_exp_f32_e32 v218, v95
	s_waitcnt lgkmcnt(0)
	s_barrier
	ds_read_b128 v[80:83], v207 offset:16384
	ds_read_b128 v[96:99], v207 offset:24576
	ds_read_b128 v[146:149], v208 offset:16384
	ds_read_b128 v[150:153], v208 offset:24576
	v_mfma_f32_32x32x16_bf16 v[48:63], v[108:111], v[220:223], v[48:63]
	v_exp_f32_e32 v154, v72
	v_exp_f32_e32 v155, v73
	v_exp_f32_e32 v156, v74
	v_exp_f32_e32 v157, v75
	v_exp_f32_e32 v158, v76
	v_exp_f32_e32 v159, v77
	v_exp_f32_e32 v160, v78
	v_exp_f32_e32 v79, v79
	s_waitcnt lgkmcnt(3)
	v_mfma_f32_32x32x16_bf16 v[80:95], v[80:83], v[142:145], 0
	v_exp_f32_e32 v236, v64
	v_add_f32_e32 v64, 0, v181
	v_add_f32_e32 v64, v183, v64
	v_add_f32_e32 v64, v184, v64
	s_waitcnt lgkmcnt(2)
	v_mfma_f32_32x32x16_bf16 v[96:111], v[96:99], v[142:145], 0
	v_add_f32_e32 v64, v185, v64
	v_add_f32_e32 v64, v186, v64
	v_add_f32_e32 v64, v187, v64
	s_waitcnt lgkmcnt(1)
	v_mfma_f32_32x32x16_bf16 v[80:95], v[146:149], v[138:141], v[80:95]
	v_add_f32_e32 v64, v188, v64
	v_add_f32_e32 v64, v189, v64
	v_add_f32_e32 v64, v196, v64
	s_waitcnt lgkmcnt(0)
	v_mfma_f32_32x32x16_bf16 v[96:111], v[150:153], v[138:141], v[96:111]
	ds_read_b128 v[146:149], v209 offset:16384
	ds_read_b128 v[150:153], v209 offset:24576
	v_add_f32_e32 v64, v197, v64
	v_add_f32_e32 v64, v198, v64
	v_add_f32_e32 v64, v199, v64
	v_add_f32_e32 v64, v215, v64
	v_exp_f32_e32 v237, v65
	s_waitcnt lgkmcnt(1)
	v_mfma_f32_32x32x16_bf16 v[80:95], v[146:149], v[112:115], v[80:95]
	v_add_f32_e32 v64, v216, v64
	v_exp_f32_e32 v238, v66
	v_add_f32_e32 v64, v217, v64
	v_exp_f32_e32 v239, v67
	s_waitcnt lgkmcnt(0)
	v_mfma_f32_32x32x16_bf16 v[96:111], v[150:153], v[112:115], v[96:111]
	ds_read_b128 v[146:149], v210 offset:16384
	ds_read_b128 v[150:153], v210 offset:24576
	v_add_f32_e32 v64, v218, v64
	v_exp_f32_e32 v247, v68
	v_add_f32_e32 v64, v236, v64
	v_exp_f32_e32 v248, v69
	s_waitcnt lgkmcnt(1)
	v_mfma_f32_32x32x16_bf16 v[80:95], v[146:149], v[116:119], v[80:95]
	v_add_f32_e32 v64, v237, v64
	v_exp_f32_e32 v249, v70
	v_add_f32_e32 v64, v238, v64
	v_exp_f32_e32 v252, v71
	s_waitcnt lgkmcnt(0)
	v_mfma_f32_32x32x16_bf16 v[96:111], v[150:153], v[116:119], v[96:111]
	ds_read_b128 v[146:149], v190 offset:16384
	ds_read_b128 v[150:153], v190 offset:24576
	v_add_f32_e32 v64, v239, v64
	v_add_f32_e32 v64, v247, v64
	v_add_f32_e32 v64, v248, v64
	v_add_f32_e32 v64, v249, v64
	v_add_f32_e32 v64, v252, v64
	v_add_f32_e32 v64, v154, v64
	s_waitcnt lgkmcnt(1)
; __device__ __forceinline__ void finishSM(f32x16& p0, f32x16& p1, float alpha, float& l_reg, bf16x8& pa0, bf16x8& pa1, bf16x8& pa2, bf16x8& pa3) {
;   for (int r = 0; r < 16; ++r) p1[r] = __builtin_amdgcn_exp2f(p1[r]);
;   float ps = 0; for (int r = 0; r < 16; ++r) ps += p0[r]; for (int r = 0; r < 16; ++r) ps += p1[r];
;   { auto rr = __builtin_amdgcn_permlane32_swap(__float_as_uint(ps), __float_as_uint(ps), false, false);
;     ps = __uint_as_float(rr[0]) + __uint_as_float(rr[1]); }
;   l_reg = l_reg * alpha + ps;
;     ...
;   PK4(p0, 0, pa0); PK4(p0, 8, pa1); PK4(p1, 0, pa2); PK4(p1, 8, pa3);
;     ...
; }
; __device__ __forceinline__ void qkt(f32x16& p0, f32x16& p1, const bf16* Ks, const bf16x8* qr, int r32, int hi) {
;   p0 = f32x16{}; p1 = f32x16{};
;   for (int d0 = 0; d0 < 8; ++d0) { int cb = (d0 * 16 + hi * 8) * 2;
;     bf16x8 b0 = *reinterpret_cast<const bf16x8*>((const char*)Ks + KSWZ(r32, cb));
;     bf16x8 b1 = *reinterpret_cast<const bf16x8*>((const char*)Ks + KSWZ(32 + r32, cb));
;     p0 = __builtin_amdgcn_mfma_f32_32x32x16_bf16(b0, qr[d0], p0, 0, 0, 0);
;     p1 = __builtin_amdgcn_mfma_f32_32x32x16_bf16(b1, qr[d0], p1, 0, 0, 0); }
; }
; __device__ __forceinline__ int v_st(int k, int c) { const int kk = (k & ~0xC) | ((k & 4) << 1) | ((k & 8) >> 1); return ((kk >> 3) * 4 + (c >> 5)) * 512 + ((kk & 7) * 32 + (c & 31)) * 2; }
; __device__ __forceinline__ int v_rd_base(int lane) { return ((lane & 3) << 3) | (((lane >> 2) & 3) << 6) | (((lane >> 4) & 1) << 5) | (((lane >> 5) & 1) << 8); }
; template <int OFF> __device__ __forceinline__ s16x4 tr_read(int vb) {
;   s16x4 r; asm volatile("ds_read_b64_tr_b16 %0, %1 offset:%2" : "=&v"(r) : "v"(vb), "i"(OFF) : "memory"); return r;
; }
; template <int D0> __device__ __forceinline__ void pv_one(f32x16& od, int vb, bf16x8 pa0, bf16x8 pa1, bf16x8 pa2, bf16x8 pa3) {
;   const s16x4 l0 = tr_read<v_rd_off(D0, 0, 0)>(vb), h0 = tr_read<v_rd_off(D0, 0, 1)>(vb), l1 = tr_read<v_rd_off(D0, 1, 0)>(vb), h1 = tr_read<v_rd_off(D0, 1, 1)>(vb);
;   const s16x4 l2 = tr_read<v_rd_off(D0, 2, 0)>(vb), h2 = tr_read<v_rd_off(D0, 2, 1)>(vb), l3 = tr_read<v_rd_off(D0, 3, 0)>(vb), h3 = tr_read<v_rd_off(D0, 3, 1)>(vb);
;   asm volatile("s_waitcnt lgkmcnt(0)" ::: "memory"); SBAR();
;     ...
;   od = __builtin_amdgcn_mfma_f32_32x32x16_bf16(pa0, PK(l0, h0), od, 0, 0, 0);
;   od = __builtin_amdgcn_mfma_f32_32x32x16_bf16(pa1, PK(l1, h1), od, 0, 0, 0);
	v_mfma_f32_32x32x16_bf16 v[80:95], v[146:149], v[120:123], v[80:95]
	v_add_f32_e32 v64, v155, v64
	v_add_f32_e32 v64, v156, v64
	v_add_f32_e32 v64, v157, v64
	v_add_f32_e32 v64, v158, v64
	v_add_f32_e32 v64, v159, v64
	s_waitcnt lgkmcnt(0)
	v_mfma_f32_32x32x16_bf16 v[96:111], v[150:153], v[120:123], v[96:111]
	ds_read_b128 v[146:149], v191 offset:16384
	ds_read_b128 v[150:153], v191 offset:24576
	v_add_f32_e32 v64, v160, v64
	v_add_f32_e32 v180, v79, v64
	v_cvt_pk_bf16_f32 v64, v181, v183
	v_cvt_pk_bf16_f32 v65, v184, v185
	v_cvt_pk_bf16_f32 v66, v186, v187
	v_cvt_pk_bf16_f32 v67, v188, v189
	s_waitcnt lgkmcnt(1)
	v_mfma_f32_32x32x16_bf16 v[80:95], v[146:149], v[124:127], v[80:95]
	v_cvt_pk_bf16_f32 v68, v196, v197
	v_cvt_pk_bf16_f32 v69, v198, v199
	v_cvt_pk_bf16_f32 v70, v215, v216
	v_cvt_pk_bf16_f32 v71, v217, v218
	v_cvt_pk_bf16_f32 v72, v236, v237
	s_waitcnt lgkmcnt(0)
	v_mfma_f32_32x32x16_bf16 v[96:111], v[150:153], v[124:127], v[96:111]
	ds_read_b128 v[146:149], v192 offset:16384
	ds_read_b128 v[150:153], v192 offset:24576
	v_cvt_pk_bf16_f32 v73, v238, v239
	v_cvt_pk_bf16_f32 v74, v247, v248
	v_cvt_pk_bf16_f32 v75, v249, v252
	v_cvt_pk_bf16_f32 v76, v154, v155
	v_cvt_pk_bf16_f32 v77, v156, v157
	v_cvt_pk_bf16_f32 v78, v158, v159
	s_waitcnt lgkmcnt(1)
	v_mfma_f32_32x32x16_bf16 v[80:95], v[146:149], v[130:133], v[80:95]
	v_cvt_pk_bf16_f32 v79, v160, v79
	v_mov_b32_e32 v182, v180
	v_permlane32_swap_b32_e32 v64, v66
	v_permlane32_swap_b32_e32 v65, v67
	v_permlane32_swap_b32_e32 v68, v70
	s_waitcnt lgkmcnt(0)
	v_mfma_f32_32x32x16_bf16 v[96:111], v[150:153], v[130:133], v[96:111]
	ds_read_b128 v[146:149], v193 offset:16384
	ds_read_b128 v[150:153], v193 offset:24576
	ds_read_b64_tr_b16 v[184:185], v206 offset:0
	ds_read_b64_tr_b16 v[186:187], v206 offset:0x800
	ds_read_b64_tr_b16 v[216:217], v206 offset:0x1000
	ds_read_b64_tr_b16 v[218:219], v206 offset:0x1800
	ds_read_b64_tr_b16 v[220:221], v206 offset:0x2000
	ds_read_b64_tr_b16 v[222:223], v206 offset:0x2800
	ds_read_b64_tr_b16 v[224:225], v206 offset:0x3000
	ds_read_b64_tr_b16 v[226:227], v206 offset:0x3800
	v_permlane32_swap_b32_e32 v69, v71
	v_permlane32_swap_b32_e32 v72, v74
	v_permlane32_swap_b32_e32 v73, v75
	v_permlane32_swap_b32_e32 v76, v78
	v_permlane32_swap_b32_e32 v77, v79
	v_permlane32_swap_b32_e32 v180, v182
	s_waitcnt lgkmcnt(9)
	v_mfma_f32_32x32x16_bf16 v[80:95], v[146:149], v[134:137], v[80:95]
	s_waitcnt lgkmcnt(8)
	v_mfma_f32_32x32x16_bf16 v[96:111], v[150:153], v[134:137], v[96:111]
	s_waitcnt vmcnt(0)
	ds_write_b128 v211, v[162:165] offset:32768
	s_waitcnt lgkmcnt(7)
	v_mfma_f32_32x32x16_bf16 v[0:15], v[64:67], v[184:187], v[0:15]
	ds_read_b64_tr_b16 v[184:185], v206 offset:0x200
	ds_read_b64_tr_b16 v[186:187], v206 offset:0xa00
	v_add_co_u32_e32 v150, vcc, s25, v178
	s_nop 1
	v_addc_co_u32_e32 v151, vcc, -1, v179, vcc
	v_add_co_u32_e32 v154, vcc, s45, v178
	s_nop 1
	v_addc_co_u32_e32 v155, vcc, -1, v179, vcc
	s_waitcnt lgkmcnt(7)
	v_mfma_f32_32x32x16_bf16 v[0:15], v[68:71], v[216:219], v[0:15]
	ds_read_b64_tr_b16 v[216:217], v206 offset:0x1200
	ds_read_b64_tr_b16 v[218:219], v206 offset:0x1a00
	global_load_dwordx4 v[146:149], v[150:151], off
	global_load_dwordx4 v[150:153], v[150:151], off offset:-512
	global_load_dwordx4 v[158:161], v[154:155], off
	global_load_dwordx4 v[154:157], v[154:155], off offset:-512
	s_waitcnt lgkmcnt(7)
	v_mfma_f32_32x32x16_bf16 v[0:15], v[72:75], v[220:223], v[0:15]
	ds_read_b64_tr_b16 v[220:221], v206 offset:0x2200
	ds_read_b64_tr_b16 v[222:223], v206 offset:0x2a00
	s_waitcnt lgkmcnt(7)
	v_mfma_f32_32x32x16_bf16 v[0:15], v[76:79], v[224:227], v[0:15]
	ds_read_b64_tr_b16 v[224:225], v206 offset:0x3200
	ds_read_b64_tr_b16 v[226:227], v206 offset:0x3a00
	ds_write_b128 v212, v[174:177] offset:32768
	s_waitcnt lgkmcnt(7)
	v_mfma_f32_32x32x16_bf16 v[16:31], v[64:67], v[184:187], v[16:31]
	ds_read_b64_tr_b16 v[184:185], v206 offset:0x400
	ds_read_b64_tr_b16 v[186:187], v206 offset:0xc00
	s_waitcnt lgkmcnt(7)
	v_mfma_f32_32x32x16_bf16 v[16:31], v[68:71], v[216:219], v[16:31]
	ds_read_b64_tr_b16 v[216:217], v206 offset:0x1400
	ds_read_b64_tr_b16 v[218:219], v206 offset:0x1c00
	s_waitcnt lgkmcnt(7)
	v_mfma_f32_32x32x16_bf16 v[16:31], v[72:75], v[220:223], v[16:31]
	ds_read_b64_tr_b16 v[220:221], v206 offset:0x2400
	ds_read_b64_tr_b16 v[222:223], v206 offset:0x2c00
	s_waitcnt lgkmcnt(7)
	v_mfma_f32_32x32x16_bf16 v[16:31], v[76:79], v[224:227], v[16:31]
	ds_read_b64_tr_b16 v[224:225], v206 offset:0x3400
	ds_read_b64_tr_b16 v[226:227], v206 offset:0x3c00
	ds_write_b128 v213, v[166:169] offset:32768
	s_waitcnt lgkmcnt(7)
	v_mfma_f32_32x32x16_bf16 v[32:47], v[64:67], v[184:187], v[32:47]
	ds_read_b64_tr_b16 v[184:185], v206 offset:0x600
	ds_read_b64_tr_b16 v[186:187], v206 offset:0xe00
	v_exp_f32_e32 v215, v90
	v_exp_f32_e32 v188, v84
	s_waitcnt lgkmcnt(7)
	v_mfma_f32_32x32x16_bf16 v[32:47], v[68:71], v[216:219], v[32:47]
	ds_read_b64_tr_b16 v[216:217], v206 offset:0x1600
	ds_read_b64_tr_b16 v[218:219], v206 offset:0x1e00
	v_exp_f32_e32 v189, v85
	v_exp_f32_e32 v196, v86
	s_waitcnt lgkmcnt(7)
	v_mfma_f32_32x32x16_bf16 v[32:47], v[72:75], v[220:223], v[32:47]
	ds_read_b64_tr_b16 v[220:221], v206 offset:0x2600
	ds_read_b64_tr_b16 v[222:223], v206 offset:0x2e00
	v_exp_f32_e32 v197, v87
	v_exp_f32_e32 v198, v88
	s_waitcnt lgkmcnt(7)
	v_mfma_f32_32x32x16_bf16 v[32:47], v[76:79], v[224:227], v[32:47]
	ds_read_b64_tr_b16 v[224:225], v206 offset:0x3600
	ds_read_b64_tr_b16 v[226:227], v206 offset:0x3e00
	v_exp_f32_e32 v199, v89
	ds_write_b128 v214, v[170:173] offset:32768
	s_waitcnt lgkmcnt(7)
	v_mfma_f32_32x32x16_bf16 v[48:63], v[64:67], v[184:187], v[48:63]
	v_exp_f32_e32 v184, v80
	v_exp_f32_e32 v185, v81
	v_exp_f32_e32 v186, v82
	v_exp_f32_e32 v187, v83
	s_waitcnt lgkmcnt(5)
	v_mfma_f32_32x32x16_bf16 v[48:63], v[68:71], v[216:219], v[48:63]
	v_exp_f32_e32 v219, v94
	v_exp_f32_e32 v216, v91
	s_waitcnt lgkmcnt(3)
	v_mfma_f32_32x32x16_bf16 v[48:63], v[72:75], v[220:223], v[48:63]
	v_exp_f32_e32 v220, v95
	v_exp_f32_e32 v217, v92
	v_exp_f32_e32 v218, v93
	s_waitcnt lgkmcnt(0)
	s_barrier
; __device__ __forceinline__ void finishSM(f32x16& p0, f32x16& p1, float alpha, float& l_reg, bf16x8& pa0, bf16x8& pa1, bf16x8& pa2, bf16x8& pa3) {
;   for (int r = 0; r < 16; ++r) p1[r] = __builtin_amdgcn_exp2f(p1[r]);
;   float ps = 0; for (int r = 0; r < 16; ++r) ps += p0[r]; for (int r = 0; r < 16; ++r) ps += p1[r];
;   { auto rr = __builtin_amdgcn_permlane32_swap(__float_as_uint(ps), __float_as_uint(ps), false, false);
;     ps = __uint_as_float(rr[0]) + __uint_as_float(rr[1]); }
;   l_reg = l_reg * alpha + ps;
;     ...
;   PK4(p0, 0, pa0); PK4(p0, 8, pa1); PK4(p1, 0, pa2); PK4(p1, 8, pa3);
;     ...
; }
; __device__ __forceinline__ void qkt(f32x16& p0, f32x16& p1, const bf16* Ks, const bf16x8* qr, int r32, int hi) {
;   p0 = f32x16{}; p1 = f32x16{};
;   for (int d0 = 0; d0 < 8; ++d0) { int cb = (d0 * 16 + hi * 8) * 2;
;     bf16x8 b0 = *reinterpret_cast<const bf16x8*>((const char*)Ks + KSWZ(r32, cb));
;     bf16x8 b1 = *reinterpret_cast<const bf16x8*>((const char*)Ks + KSWZ(32 + r32, cb));
;     p0 = __builtin_amdgcn_mfma_f32_32x32x16_bf16(b0, qr[d0], p0, 0, 0, 0);
;     p1 = __builtin_amdgcn_mfma_f32_32x32x16_bf16(b1, qr[d0], p1, 0, 0, 0); }
; }
; __device__ __forceinline__ int v_st(int k, int c) { const int kk = (k & ~0xC) | ((k & 4) << 1) | ((k & 8) >> 1); return ((kk >> 3) * 4 + (c >> 5)) * 512 + ((kk & 7) * 32 + (c & 31)) * 2; }
; __device__ __forceinline__ int v_rd_base(int lane) { return ((lane & 3) << 3) | (((lane >> 2) & 3) << 6) | (((lane >> 4) & 1) << 5) | (((lane >> 5) & 1) << 8); }
; template <int OFF> __device__ __forceinline__ s16x4 tr_read(int vb) {
;   s16x4 r; asm volatile("ds_read_b64_tr_b16 %0, %1 offset:%2" : "=&v"(r) : "v"(vb), "i"(OFF) : "memory"); return r;
; }
; template <int D0> __device__ __forceinline__ void pv_one(f32x16& od, int vb, bf16x8 pa0, bf16x8 pa1, bf16x8 pa2, bf16x8 pa3) {
;   const s16x4 l0 = tr_read<v_rd_off(D0, 0, 0)>(vb), h0 = tr_read<v_rd_off(D0, 0, 1)>(vb), l1 = tr_read<v_rd_off(D0, 1, 0)>(vb), h1 = tr_read<v_rd_off(D0, 1, 1)>(vb);
;   const s16x4 l2 = tr_read<v_rd_off(D0, 2, 0)>(vb), h2 = tr_read<v_rd_off(D0, 2, 1)>(vb), l3 = tr_read<v_rd_off(D0, 3, 0)>(vb), h3 = tr_read<v_rd_off(D0, 3, 1)>(vb);
;   asm volatile("s_waitcnt lgkmcnt(0)" ::: "memory"); SBAR();
;     ...
;   od = __builtin_amdgcn_mfma_f32_32x32x16_bf16(pa0, PK(l0, h0), od, 0, 0, 0);
;   od = __builtin_amdgcn_mfma_f32_32x32x16_bf16(pa1, PK(l1, h1), od, 0, 0, 0);
	ds_read_b128 v[64:67], v207 offset:32768
	ds_read_b128 v[80:83], v207 offset:40960
	ds_read_b128 v[162:165], v208 offset:32768
	ds_read_b128 v[166:169], v208 offset:40960
	v_mfma_f32_32x32x16_bf16 v[48:63], v[76:79], v[224:227], v[48:63]
	v_exp_f32_e32 v170, v104
	v_exp_f32_e32 v171, v105
	v_exp_f32_e32 v172, v106
	v_exp_f32_e32 v173, v107
	v_exp_f32_e32 v174, v108
	v_exp_f32_e32 v175, v109
	v_exp_f32_e32 v176, v110
	v_exp_f32_e32 v111, v111
	s_waitcnt lgkmcnt(3)
	v_mfma_f32_32x32x16_bf16 v[64:79], v[64:67], v[142:145], 0
	v_exp_f32_e32 v236, v96
	v_add_f32_e32 v96, 0, v184
	v_add_f32_e32 v96, v185, v96
	v_add_f32_e32 v96, v186, v96
	s_waitcnt lgkmcnt(2)
	v_mfma_f32_32x32x16_bf16 v[80:95], v[80:83], v[142:145], 0
	v_add_f32_e32 v96, v187, v96
	v_add_f32_e32 v96, v188, v96
	v_add_f32_e32 v96, v189, v96
	s_waitcnt lgkmcnt(1)
	v_mfma_f32_32x32x16_bf16 v[64:79], v[162:165], v[138:141], v[64:79]
	v_add_f32_e32 v96, v196, v96
	v_add_f32_e32 v96, v197, v96
	v_add_f32_e32 v96, v198, v96
	s_waitcnt lgkmcnt(0)
	v_mfma_f32_32x32x16_bf16 v[80:95], v[166:169], v[138:141], v[80:95]
	ds_read_b128 v[162:165], v209 offset:32768
	ds_read_b128 v[166:169], v209 offset:40960
	v_add_f32_e32 v96, v199, v96
	v_add_f32_e32 v96, v215, v96
	v_add_f32_e32 v96, v216, v96
	v_add_f32_e32 v96, v217, v96
	v_exp_f32_e32 v237, v97
	s_waitcnt lgkmcnt(1)
	v_mfma_f32_32x32x16_bf16 v[64:79], v[162:165], v[112:115], v[64:79]
	v_add_f32_e32 v96, v218, v96
	v_exp_f32_e32 v238, v98
	v_add_f32_e32 v96, v219, v96
	v_exp_f32_e32 v239, v99
	s_waitcnt lgkmcnt(0)
	v_mfma_f32_32x32x16_bf16 v[80:95], v[166:169], v[112:115], v[80:95]
	ds_read_b128 v[162:165], v210 offset:32768
	ds_read_b128 v[166:169], v210 offset:40960
	v_add_f32_e32 v96, v220, v96
	v_exp_f32_e32 v247, v100
	v_add_f32_e32 v96, v236, v96
	v_exp_f32_e32 v248, v101
	s_waitcnt lgkmcnt(1)
	v_mfma_f32_32x32x16_bf16 v[64:79], v[162:165], v[116:119], v[64:79]
	v_add_f32_e32 v96, v237, v96
	v_exp_f32_e32 v249, v102
	v_add_f32_e32 v96, v238, v96
	v_exp_f32_e32 v252, v103
	s_waitcnt lgkmcnt(0)
	v_mfma_f32_32x32x16_bf16 v[80:95], v[166:169], v[116:119], v[80:95]
	ds_read_b128 v[162:165], v190 offset:32768
	ds_read_b128 v[166:169], v190 offset:40960
	v_add_f32_e32 v96, v239, v96
	v_add_f32_e32 v96, v247, v96
	v_add_f32_e32 v96, v248, v96
	v_add_f32_e32 v96, v249, v96
	v_add_f32_e32 v96, v252, v96
	v_add_f32_e32 v96, v170, v96
	s_waitcnt lgkmcnt(1)
	v_mfma_f32_32x32x16_bf16 v[64:79], v[162:165], v[120:123], v[64:79]
	v_add_f32_e32 v96, v171, v96
	v_add_f32_e32 v96, v172, v96
	v_add_f32_e32 v96, v173, v96
	v_add_f32_e32 v96, v174, v96
	v_add_f32_e32 v96, v175, v96
	s_waitcnt lgkmcnt(0)
	v_mfma_f32_32x32x16_bf16 v[80:95], v[166:169], v[120:123], v[80:95]
	ds_read_b128 v[162:165], v191 offset:32768
	ds_read_b128 v[166:169], v191 offset:40960
	v_add_f32_e32 v96, v176, v96
	v_add_f32_e32 v181, v111, v96
	v_mov_b32_e32 v183, v181
	s_nop 1
	v_permlane32_swap_b32_e32 v181, v183
	v_pk_add_f32 v[96:97], v[180:181], v[182:183]
	s_waitcnt lgkmcnt(1)
	v_mfma_f32_32x32x16_bf16 v[64:79], v[162:165], v[124:127], v[64:79]
	s_nop 0
	v_add_f32_e32 v96, v128, v96
	v_add_f32_e32 v128, v96, v97
	v_cvt_pk_bf16_f32 v96, v184, v185
	v_cvt_pk_bf16_f32 v97, v186, v187
	s_waitcnt lgkmcnt(0)
	v_mfma_f32_32x32x16_bf16 v[80:95], v[166:169], v[124:127], v[80:95]
	ds_read_b128 v[162:165], v192 offset:32768
	ds_read_b128 v[166:169], v192 offset:40960
	v_cvt_pk_bf16_f32 v98, v188, v189
	v_cvt_pk_bf16_f32 v99, v196, v197
	v_cvt_pk_bf16_f32 v100, v198, v199
	v_cvt_pk_bf16_f32 v101, v215, v216
	v_cvt_pk_bf16_f32 v102, v217, v218
	v_cvt_pk_bf16_f32 v103, v219, v220
	s_waitcnt lgkmcnt(1)
	v_mfma_f32_32x32x16_bf16 v[64:79], v[162:165], v[130:133], v[64:79]
	v_cvt_pk_bf16_f32 v104, v236, v237
	v_cvt_pk_bf16_f32 v105, v238, v239
	v_cvt_pk_bf16_f32 v106, v247, v248
	v_cvt_pk_bf16_f32 v107, v249, v252
	v_cvt_pk_bf16_f32 v108, v170, v171
	s_waitcnt lgkmcnt(0)
	v_mfma_f32_32x32x16_bf16 v[80:95], v[166:169], v[130:133], v[80:95]
	ds_read_b128 v[162:165], v193 offset:32768
	ds_read_b128 v[166:169], v193 offset:40960
	ds_read_b64_tr_b16 v[180:181], v206 offset:0x4000
	ds_read_b64_tr_b16 v[182:183], v206 offset:0x4800
	ds_read_b64_tr_b16 v[184:185], v206 offset:0x5000
	ds_read_b64_tr_b16 v[186:187], v206 offset:0x5800
	ds_read_b64_tr_b16 v[216:217], v206 offset:0x6000
	ds_read_b64_tr_b16 v[218:219], v206 offset:0x6800
	ds_read_b64_tr_b16 v[220:221], v206 offset:0x7000
	ds_read_b64_tr_b16 v[222:223], v206 offset:0x7800
	v_cvt_pk_bf16_f32 v109, v172, v173
	v_cvt_pk_bf16_f32 v110, v174, v175
	v_cvt_pk_bf16_f32 v111, v176, v111
	s_nop 0
	v_permlane32_swap_b32_e32 v96, v98
	v_permlane32_swap_b32_e32 v97, v99
	s_waitcnt lgkmcnt(9)
	v_mfma_f32_32x32x16_bf16 v[64:79], v[162:165], v[134:137], v[64:79]
	v_permlane32_swap_b32_e32 v100, v102
	v_permlane32_swap_b32_e32 v101, v103
	v_permlane32_swap_b32_e32 v104, v106
	v_permlane32_swap_b32_e32 v105, v107
	v_permlane32_swap_b32_e32 v108, v110
	s_waitcnt lgkmcnt(8)
	v_mfma_f32_32x32x16_bf16 v[80:95], v[166:169], v[134:137], v[80:95]
	v_permlane32_swap_b32_e32 v109, v111
	s_waitcnt vmcnt(0)
	ds_write_b128 v211, v[146:149]
	s_waitcnt lgkmcnt(7)
	v_mfma_f32_32x32x16_bf16 v[0:15], v[96:99], v[180:183], v[0:15]
	ds_read_b64_tr_b16 v[180:181], v206 offset:0x4200
	ds_read_b64_tr_b16 v[182:183], v206 offset:0x4a00
	v_add_co_u32_e32 v166, vcc, s52, v178
	s_nop 1
	v_addc_co_u32_e32 v167, vcc, -1, v179, vcc
	v_add_co_u32_e32 v170, vcc, s53, v178
	s_nop 1
	v_addc_co_u32_e32 v171, vcc, -1, v179, vcc
	s_waitcnt lgkmcnt(7)
; __device__ __forceinline__ void finishSM(f32x16& p0, f32x16& p1, float alpha, float& l_reg, bf16x8& pa0, bf16x8& pa1, bf16x8& pa2, bf16x8& pa3) {
;   for (int r = 0; r < 16; ++r) p1[r] = __builtin_amdgcn_exp2f(p1[r]);
;   float ps = 0; for (int r = 0; r < 16; ++r) ps += p0[r]; for (int r = 0; r < 16; ++r) ps += p1[r];
;   { auto rr = __builtin_amdgcn_permlane32_swap(__float_as_uint(ps), __float_as_uint(ps), false, false);
;     ps = __uint_as_float(rr[0]) + __uint_as_float(rr[1]); }
;   l_reg = l_reg * alpha + ps;
;     ...
;   PK4(p0, 0, pa0); PK4(p0, 8, pa1); PK4(p1, 0, pa2); PK4(p1, 8, pa3);
;     ...
; }
; __device__ __forceinline__ void qkt(f32x16& p0, f32x16& p1, const bf16* Ks, const bf16x8* qr, int r32, int hi) {
;   p0 = f32x16{}; p1 = f32x16{};
;   for (int d0 = 0; d0 < 8; ++d0) { int cb = (d0 * 16 + hi * 8) * 2;
;     bf16x8 b0 = *reinterpret_cast<const bf16x8*>((const char*)Ks + KSWZ(r32, cb));
;     bf16x8 b1 = *reinterpret_cast<const bf16x8*>((const char*)Ks + KSWZ(32 + r32, cb));
;     p0 = __builtin_amdgcn_mfma_f32_32x32x16_bf16(b0, qr[d0], p0, 0, 0, 0);
;     p1 = __builtin_amdgcn_mfma_f32_32x32x16_bf16(b1, qr[d0], p1, 0, 0, 0); }
; }
; __device__ __forceinline__ int v_st(int k, int c) { const int kk = (k & ~0xC) | ((k & 4) << 1) | ((k & 8) >> 1); return ((kk >> 3) * 4 + (c >> 5)) * 512 + ((kk & 7) * 32 + (c & 31)) * 2; }
; __device__ __forceinline__ int v_rd_base(int lane) { return ((lane & 3) << 3) | (((lane >> 2) & 3) << 6) | (((lane >> 4) & 1) << 5) | (((lane >> 5) & 1) << 8); }
; template <int OFF> __device__ __forceinline__ s16x4 tr_read(int vb) {
;   s16x4 r; asm volatile("ds_read_b64_tr_b16 %0, %1 offset:%2" : "=&v"(r) : "v"(vb), "i"(OFF) : "memory"); return r;
; }
; template <int D0> __device__ __forceinline__ void pv_one(f32x16& od, int vb, bf16x8 pa0, bf16x8 pa1, bf16x8 pa2, bf16x8 pa3) {
;   const s16x4 l0 = tr_read<v_rd_off(D0, 0, 0)>(vb), h0 = tr_read<v_rd_off(D0, 0, 1)>(vb), l1 = tr_read<v_rd_off(D0, 1, 0)>(vb), h1 = tr_read<v_rd_off(D0, 1, 1)>(vb);
;   const s16x4 l2 = tr_read<v_rd_off(D0, 2, 0)>(vb), h2 = tr_read<v_rd_off(D0, 2, 1)>(vb), l3 = tr_read<v_rd_off(D0, 3, 0)>(vb), h3 = tr_read<v_rd_off(D0, 3, 1)>(vb);
;   asm volatile("s_waitcnt lgkmcnt(0)" ::: "memory"); SBAR();
;     ...
;   od = __builtin_amdgcn_mfma_f32_32x32x16_bf16(pa0, PK(l0, h0), od, 0, 0, 0);
;   od = __builtin_amdgcn_mfma_f32_32x32x16_bf16(pa1, PK(l1, h1), od, 0, 0, 0);
	v_mfma_f32_32x32x16_bf16 v[0:15], v[100:103], v[184:187], v[0:15]
	ds_read_b64_tr_b16 v[184:185], v206 offset:0x5200
	ds_read_b64_tr_b16 v[186:187], v206 offset:0x5a00
	global_load_dwordx4 v[162:165], v[166:167], off
	global_load_dwordx4 v[166:169], v[166:167], off offset:-512
	global_load_dwordx4 v[174:177], v[170:171], off
	global_load_dwordx4 v[170:173], v[170:171], off offset:-512
	s_waitcnt lgkmcnt(7)
	v_mfma_f32_32x32x16_bf16 v[0:15], v[104:107], v[216:219], v[0:15]
	ds_read_b64_tr_b16 v[216:217], v206 offset:0x6200
	ds_read_b64_tr_b16 v[218:219], v206 offset:0x6a00
	s_waitcnt lgkmcnt(7)
	v_mfma_f32_32x32x16_bf16 v[0:15], v[108:111], v[220:223], v[0:15]
	ds_read_b64_tr_b16 v[220:221], v206 offset:0x7200
	ds_read_b64_tr_b16 v[222:223], v206 offset:0x7a00
	ds_write_b128 v212, v[158:161]
	s_waitcnt lgkmcnt(7)
	v_mfma_f32_32x32x16_bf16 v[16:31], v[96:99], v[180:183], v[16:31]
	ds_read_b64_tr_b16 v[180:181], v206 offset:0x4400
	ds_read_b64_tr_b16 v[182:183], v206 offset:0x4c00
	s_waitcnt lgkmcnt(7)
	v_mfma_f32_32x32x16_bf16 v[16:31], v[100:103], v[184:187], v[16:31]
	ds_read_b64_tr_b16 v[184:185], v206 offset:0x5400
	ds_read_b64_tr_b16 v[186:187], v206 offset:0x5c00
	s_waitcnt lgkmcnt(7)
	v_mfma_f32_32x32x16_bf16 v[16:31], v[104:107], v[216:219], v[16:31]
	ds_read_b64_tr_b16 v[216:217], v206 offset:0x6400
	ds_read_b64_tr_b16 v[218:219], v206 offset:0x6c00
	s_waitcnt lgkmcnt(7)
	v_mfma_f32_32x32x16_bf16 v[16:31], v[108:111], v[220:223], v[16:31]
	ds_read_b64_tr_b16 v[220:221], v206 offset:0x7400
	ds_read_b64_tr_b16 v[222:223], v206 offset:0x7c00
	ds_write_b128 v213, v[150:153]
	s_waitcnt lgkmcnt(7)
	v_mfma_f32_32x32x16_bf16 v[32:47], v[96:99], v[180:183], v[32:47]
	ds_read_b64_tr_b16 v[180:181], v206 offset:0x4600
	ds_read_b64_tr_b16 v[182:183], v206 offset:0x4e00
	v_exp_f32_e32 v188, v72
	v_exp_f32_e32 v189, v73
	s_waitcnt lgkmcnt(7)
	v_mfma_f32_32x32x16_bf16 v[32:47], v[100:103], v[184:187], v[32:47]
	ds_read_b64_tr_b16 v[184:185], v206 offset:0x5600
	ds_read_b64_tr_b16 v[186:187], v206 offset:0x5e00
	v_exp_f32_e32 v196, v74
	v_exp_f32_e32 v197, v75
	s_waitcnt lgkmcnt(7)
	v_mfma_f32_32x32x16_bf16 v[32:47], v[104:107], v[216:219], v[32:47]
	ds_read_b64_tr_b16 v[216:217], v206 offset:0x6600
	ds_read_b64_tr_b16 v[218:219], v206 offset:0x6e00
	v_exp_f32_e32 v198, v76
	v_exp_f32_e32 v199, v77
	s_waitcnt lgkmcnt(7)
	v_mfma_f32_32x32x16_bf16 v[32:47], v[108:111], v[220:223], v[32:47]
	ds_read_b64_tr_b16 v[220:221], v206 offset:0x7600
	ds_read_b64_tr_b16 v[222:223], v206 offset:0x7e00
	ds_write_b128 v214, v[154:157]
	s_waitcnt lgkmcnt(7)
	v_mfma_f32_32x32x16_bf16 v[48:63], v[96:99], v[180:183], v[48:63]
	v_exp_f32_e32 v180, v64
	v_exp_f32_e32 v181, v65
	v_exp_f32_e32 v182, v66
	v_exp_f32_e32 v183, v67
	s_waitcnt lgkmcnt(5)
	v_mfma_f32_32x32x16_bf16 v[48:63], v[100:103], v[184:187], v[48:63]
	v_exp_f32_e32 v184, v68
	v_exp_f32_e32 v185, v69
	v_exp_f32_e32 v186, v70
	v_exp_f32_e32 v187, v71
	s_waitcnt lgkmcnt(3)
	v_mfma_f32_32x32x16_bf16 v[48:63], v[104:107], v[216:219], v[48:63]
	v_exp_f32_e32 v216, v78
	v_exp_f32_e32 v217, v79
	s_waitcnt lgkmcnt(0)
	s_barrier
	ds_read_b128 v[64:67], v207
	ds_read_b128 v[68:71], v207 offset:8192
	ds_read_b128 v[146:149], v208
	ds_read_b128 v[150:153], v208 offset:8192
	v_mfma_f32_32x32x16_bf16 v[48:63], v[108:111], v[220:223], v[48:63]
	v_exp_f32_e32 v154, v88
	v_exp_f32_e32 v155, v89
	v_exp_f32_e32 v156, v90
	v_exp_f32_e32 v157, v91
	v_exp_f32_e32 v158, v92
	v_exp_f32_e32 v159, v93
	v_exp_f32_e32 v160, v94
	v_exp_f32_e32 v95, v95
	s_waitcnt lgkmcnt(3)
	v_mfma_f32_32x32x16_bf16 v[96:111], v[64:67], v[142:145], 0
	v_exp_f32_e32 v236, v80
	v_add_f32_e32 v80, 0, v180
	v_add_f32_e32 v80, v181, v80
	v_add_f32_e32 v80, v182, v80
	s_waitcnt lgkmcnt(2)
	v_mfma_f32_32x32x16_bf16 v[64:79], v[68:71], v[142:145], 0
	v_add_f32_e32 v80, v183, v80
	v_add_f32_e32 v80, v184, v80
	v_add_f32_e32 v80, v185, v80
	s_waitcnt lgkmcnt(1)
	v_mfma_f32_32x32x16_bf16 v[96:111], v[146:149], v[138:141], v[96:111]
	v_add_f32_e32 v80, v186, v80
	v_add_f32_e32 v80, v187, v80
	v_add_f32_e32 v80, v188, v80
	s_waitcnt lgkmcnt(0)
	v_mfma_f32_32x32x16_bf16 v[64:79], v[150:153], v[138:141], v[64:79]
	ds_read_b128 v[146:149], v209
	ds_read_b128 v[150:153], v209 offset:8192
	v_add_f32_e32 v80, v189, v80
	v_add_f32_e32 v80, v196, v80
	v_add_f32_e32 v80, v197, v80
	v_add_f32_e32 v80, v198, v80
	v_exp_f32_e32 v237, v81
	s_waitcnt lgkmcnt(1)
	v_mfma_f32_32x32x16_bf16 v[96:111], v[146:149], v[112:115], v[96:111]
	v_add_f32_e32 v80, v199, v80
	v_exp_f32_e32 v238, v82
	v_add_f32_e32 v80, v216, v80
	v_exp_f32_e32 v239, v83
	s_waitcnt lgkmcnt(0)
	v_mfma_f32_32x32x16_bf16 v[64:79], v[150:153], v[112:115], v[64:79]
	ds_read_b128 v[146:149], v210
	ds_read_b128 v[150:153], v210 offset:8192
	v_add_f32_e32 v80, v217, v80
	v_exp_f32_e32 v247, v84
	v_add_f32_e32 v80, v236, v80
	v_exp_f32_e32 v248, v85
	s_waitcnt lgkmcnt(1)
	v_mfma_f32_32x32x16_bf16 v[96:111], v[146:149], v[116:119], v[96:111]
	v_add_f32_e32 v80, v237, v80
	v_exp_f32_e32 v249, v86
	v_add_f32_e32 v80, v238, v80
	v_exp_f32_e32 v252, v87
	s_waitcnt lgkmcnt(0)
	v_mfma_f32_32x32x16_bf16 v[64:79], v[150:153], v[116:119], v[64:79]
	ds_read_b128 v[146:149], v190 offset:0
	ds_read_b128 v[150:153], v190 offset:8192
	v_add_f32_e32 v80, v239, v80
	v_add_f32_e32 v80, v247, v80
	v_add_f32_e32 v80, v248, v80
	v_add_f32_e32 v80, v249, v80
	v_add_f32_e32 v80, v252, v80
	v_add_f32_e32 v80, v154, v80
	s_waitcnt lgkmcnt(1)
	v_mfma_f32_32x32x16_bf16 v[96:111], v[146:149], v[120:123], v[96:111]
	v_add_f32_e32 v80, v155, v80
	v_add_f32_e32 v80, v156, v80
	v_add_f32_e32 v80, v157, v80
	v_add_f32_e32 v80, v158, v80
	v_add_f32_e32 v80, v159, v80
	s_waitcnt lgkmcnt(0)
; __device__ __forceinline__ void finishSM(f32x16& p0, f32x16& p1, float alpha, float& l_reg, bf16x8& pa0, bf16x8& pa1, bf16x8& pa2, bf16x8& pa3) {
;   for (int r = 0; r < 16; ++r) p1[r] = __builtin_amdgcn_exp2f(p1[r]);
;   float ps = 0; for (int r = 0; r < 16; ++r) ps += p0[r]; for (int r = 0; r < 16; ++r) ps += p1[r];
;   { auto rr = __builtin_amdgcn_permlane32_swap(__float_as_uint(ps), __float_as_uint(ps), false, false);
;     ps = __uint_as_float(rr[0]) + __uint_as_float(rr[1]); }
;   l_reg = l_reg * alpha + ps;
;     ...
;   PK4(p0, 0, pa0); PK4(p0, 8, pa1); PK4(p1, 0, pa2); PK4(p1, 8, pa3);
;     ...
; }
; __device__ __forceinline__ void qkt(f32x16& p0, f32x16& p1, const bf16* Ks, const bf16x8* qr, int r32, int hi) {
;   p0 = f32x16{}; p1 = f32x16{};
;   for (int d0 = 0; d0 < 8; ++d0) { int cb = (d0 * 16 + hi * 8) * 2;
;     bf16x8 b0 = *reinterpret_cast<const bf16x8*>((const char*)Ks + KSWZ(r32, cb));
;     bf16x8 b1 = *reinterpret_cast<const bf16x8*>((const char*)Ks + KSWZ(32 + r32, cb));
;     p0 = __builtin_amdgcn_mfma_f32_32x32x16_bf16(b0, qr[d0], p0, 0, 0, 0);
;     p1 = __builtin_amdgcn_mfma_f32_32x32x16_bf16(b1, qr[d0], p1, 0, 0, 0); }
; }
; __device__ __forceinline__ int v_st(int k, int c) { const int kk = (k & ~0xC) | ((k & 4) << 1) | ((k & 8) >> 1); return ((kk >> 3) * 4 + (c >> 5)) * 512 + ((kk & 7) * 32 + (c & 31)) * 2; }
; __device__ __forceinline__ int v_rd_base(int lane) { return ((lane & 3) << 3) | (((lane >> 2) & 3) << 6) | (((lane >> 4) & 1) << 5) | (((lane >> 5) & 1) << 8); }
; template <int OFF> __device__ __forceinline__ s16x4 tr_read(int vb) {
;   s16x4 r; asm volatile("ds_read_b64_tr_b16 %0, %1 offset:%2" : "=&v"(r) : "v"(vb), "i"(OFF) : "memory"); return r;
; }
; template <int D0> __device__ __forceinline__ void pv_one(f32x16& od, int vb, bf16x8 pa0, bf16x8 pa1, bf16x8 pa2, bf16x8 pa3) {
;   const s16x4 l0 = tr_read<v_rd_off(D0, 0, 0)>(vb), h0 = tr_read<v_rd_off(D0, 0, 1)>(vb), l1 = tr_read<v_rd_off(D0, 1, 0)>(vb), h1 = tr_read<v_rd_off(D0, 1, 1)>(vb);
;   const s16x4 l2 = tr_read<v_rd_off(D0, 2, 0)>(vb), h2 = tr_read<v_rd_off(D0, 2, 1)>(vb), l3 = tr_read<v_rd_off(D0, 3, 0)>(vb), h3 = tr_read<v_rd_off(D0, 3, 1)>(vb);
;   asm volatile("s_waitcnt lgkmcnt(0)" ::: "memory"); SBAR();
;     ...
;   od = __builtin_amdgcn_mfma_f32_32x32x16_bf16(pa0, PK(l0, h0), od, 0, 0, 0);
;   od = __builtin_amdgcn_mfma_f32_32x32x16_bf16(pa1, PK(l1, h1), od, 0, 0, 0);
	v_mfma_f32_32x32x16_bf16 v[64:79], v[150:153], v[120:123], v[64:79]
	ds_read_b128 v[146:149], v191 offset:0
	ds_read_b128 v[150:153], v191 offset:8192
	v_add_f32_e32 v80, v160, v80
	v_add_f32_e32 v80, v95, v80
	v_mov_b32_e32 v81, v80
	s_nop 1
	v_permlane32_swap_b32_e32 v80, v81
	v_add_f32_e32 v80, v80, v81
	s_waitcnt lgkmcnt(1)
	v_mfma_f32_32x32x16_bf16 v[96:111], v[146:149], v[124:127], v[96:111]
	v_add_f32_e32 v215, v128, v80
	v_cvt_pk_bf16_f32 v80, v180, v181
	v_cvt_pk_bf16_f32 v81, v182, v183
	v_cvt_pk_bf16_f32 v82, v184, v185
	v_cvt_pk_bf16_f32 v83, v186, v187
	s_waitcnt lgkmcnt(0)
	v_mfma_f32_32x32x16_bf16 v[64:79], v[150:153], v[124:127], v[64:79]
	ds_read_b128 v[146:149], v192 offset:0
	ds_read_b128 v[150:153], v192 offset:8192
	v_cvt_pk_bf16_f32 v84, v188, v189
	v_cvt_pk_bf16_f32 v85, v196, v197
	v_cvt_pk_bf16_f32 v86, v198, v199
	v_cvt_pk_bf16_f32 v87, v216, v217
	v_cvt_pk_bf16_f32 v88, v236, v237
	v_cvt_pk_bf16_f32 v89, v238, v239
	s_waitcnt lgkmcnt(1)
	v_mfma_f32_32x32x16_bf16 v[96:111], v[146:149], v[130:133], v[96:111]
	v_cvt_pk_bf16_f32 v90, v247, v248
	v_cvt_pk_bf16_f32 v91, v249, v252
	v_cvt_pk_bf16_f32 v92, v154, v155
	v_cvt_pk_bf16_f32 v93, v156, v157
	v_cvt_pk_bf16_f32 v94, v158, v159
	s_waitcnt lgkmcnt(0)
	v_mfma_f32_32x32x16_bf16 v[64:79], v[150:153], v[130:133], v[64:79]
	ds_read_b128 v[146:149], v193 offset:0
	ds_read_b128 v[150:153], v193 offset:8192
	ds_read_b64_tr_b16 v[180:181], v206 offset:0x8000
	ds_read_b64_tr_b16 v[182:183], v206 offset:0x8800
	ds_read_b64_tr_b16 v[184:185], v206 offset:0x9000
	ds_read_b64_tr_b16 v[186:187], v206 offset:0x9800
	ds_read_b64_tr_b16 v[216:217], v206 offset:0xa000
	ds_read_b64_tr_b16 v[218:219], v206 offset:0xa800
	ds_read_b64_tr_b16 v[220:221], v206 offset:0xb000
	ds_read_b64_tr_b16 v[222:223], v206 offset:0xb800
	v_cvt_pk_bf16_f32 v95, v160, v95
	s_nop 0
	v_permlane32_swap_b32_e32 v80, v82
	v_permlane32_swap_b32_e32 v81, v83
	v_permlane32_swap_b32_e32 v84, v86
	v_permlane32_swap_b32_e32 v85, v87
	s_waitcnt lgkmcnt(9)
	v_mfma_f32_32x32x16_bf16 v[96:111], v[146:149], v[134:137], v[96:111]
	v_permlane32_swap_b32_e32 v88, v90
	v_permlane32_swap_b32_e32 v89, v91
	v_permlane32_swap_b32_e32 v92, v94
	v_permlane32_swap_b32_e32 v93, v95
	s_waitcnt lgkmcnt(8)
	v_mfma_f32_32x32x16_bf16 v[64:79], v[150:153], v[134:137], v[64:79]
	s_waitcnt vmcnt(0)
	ds_write_b128 v211, v[162:165] offset:16384
	s_waitcnt lgkmcnt(7)
	v_mfma_f32_32x32x16_bf16 v[0:15], v[80:83], v[180:183], v[0:15]
	ds_read_b64_tr_b16 v[180:181], v206 offset:0x8200
	ds_read_b64_tr_b16 v[182:183], v206 offset:0x8a00
	v_add_co_u32_e32 v150, vcc, s58, v178
	s_nop 1
	v_addc_co_u32_e32 v151, vcc, -1, v179, vcc
	s_waitcnt lgkmcnt(7)
	v_mfma_f32_32x32x16_bf16 v[0:15], v[84:87], v[184:187], v[0:15]
	ds_read_b64_tr_b16 v[184:185], v206 offset:0x9200
	ds_read_b64_tr_b16 v[186:187], v206 offset:0x9a00
	global_load_dwordx4 v[146:149], v[150:151], off
	global_load_dwordx4 v[154:157], v[150:151], off offset:-512
	global_load_dwordx4 v[150:153], v[178:179], off
	global_load_dwordx4 v[158:161], v[178:179], off offset:-512
	s_waitcnt lgkmcnt(7)
	v_mfma_f32_32x32x16_bf16 v[0:15], v[88:91], v[216:219], v[0:15]
	ds_read_b64_tr_b16 v[216:217], v206 offset:0xa200
	ds_read_b64_tr_b16 v[218:219], v206 offset:0xaa00
	s_waitcnt lgkmcnt(7)
	v_mfma_f32_32x32x16_bf16 v[0:15], v[92:95], v[220:223], v[0:15]
	ds_read_b64_tr_b16 v[220:221], v206 offset:0xb200
	ds_read_b64_tr_b16 v[222:223], v206 offset:0xba00
	ds_write_b128 v212, v[174:177] offset:16384
	s_waitcnt lgkmcnt(7)
	v_mfma_f32_32x32x16_bf16 v[16:31], v[80:83], v[180:183], v[16:31]
	ds_read_b64_tr_b16 v[180:181], v206 offset:0x8400
	ds_read_b64_tr_b16 v[182:183], v206 offset:0x8c00
	s_waitcnt lgkmcnt(7)
	v_mfma_f32_32x32x16_bf16 v[16:31], v[84:87], v[184:187], v[16:31]
	ds_read_b64_tr_b16 v[184:185], v206 offset:0x9400
	ds_read_b64_tr_b16 v[186:187], v206 offset:0x9c00
	s_waitcnt lgkmcnt(7)
	v_mfma_f32_32x32x16_bf16 v[16:31], v[88:91], v[216:219], v[16:31]
	ds_read_b64_tr_b16 v[216:217], v206 offset:0xa400
	ds_read_b64_tr_b16 v[218:219], v206 offset:0xac00
	s_waitcnt lgkmcnt(7)
	v_mfma_f32_32x32x16_bf16 v[16:31], v[92:95], v[220:223], v[16:31]
	ds_read_b64_tr_b16 v[220:221], v206 offset:0xb400
	ds_read_b64_tr_b16 v[222:223], v206 offset:0xbc00
	ds_write_b128 v213, v[166:169] offset:16384
	s_waitcnt lgkmcnt(7)
	v_mfma_f32_32x32x16_bf16 v[32:47], v[80:83], v[180:183], v[32:47]
	ds_read_b64_tr_b16 v[180:181], v206 offset:0x8600
	ds_read_b64_tr_b16 v[182:183], v206 offset:0x8e00
	v_exp_f32_e32 v229, v96
	v_exp_f32_e32 v243, v97
	s_waitcnt lgkmcnt(7)
	v_mfma_f32_32x32x16_bf16 v[32:47], v[84:87], v[184:187], v[32:47]
	ds_read_b64_tr_b16 v[184:185], v206 offset:0x9600
	ds_read_b64_tr_b16 v[186:187], v206 offset:0x9e00
	v_exp_f32_e32 v244, v98
	v_exp_f32_e32 v246, v99
	s_waitcnt lgkmcnt(7)
	v_mfma_f32_32x32x16_bf16 v[32:47], v[88:91], v[216:219], v[32:47]
	ds_read_b64_tr_b16 v[216:217], v206 offset:0xa600
	ds_read_b64_tr_b16 v[218:219], v206 offset:0xae00
	v_exp_f32_e32 v242, v100
	v_exp_f32_e32 v245, v101
	s_waitcnt lgkmcnt(7)
	v_mfma_f32_32x32x16_bf16 v[32:47], v[92:95], v[220:223], v[32:47]
	ds_read_b64_tr_b16 v[220:221], v206 offset:0xb600
	ds_read_b64_tr_b16 v[222:223], v206 offset:0xbe00
	v_exp_f32_e32 v227, v102
	v_exp_f32_e32 v228, v103
	ds_write_b128 v214, v[170:173] offset:16384
	s_waitcnt lgkmcnt(7)
	v_mfma_f32_32x32x16_bf16 v[48:63], v[80:83], v[180:183], v[48:63]
	s_waitcnt lgkmcnt(5)
	v_mfma_f32_32x32x16_bf16 v[48:63], v[84:87], v[184:187], v[48:63]
	v_exp_f32_e32 v226, v105
	v_exp_f32_e32 v224, v106
	v_exp_f32_e32 v225, v107
	s_add_i32 s28, s28, 6
	v_lshl_add_u64 v[178:179], v[178:179], 0, s[60:61]
	s_waitcnt lgkmcnt(3)
	v_mfma_f32_32x32x16_bf16 v[48:63], v[88:91], v[216:219], v[48:63]
	v_exp_f32_e32 v219, v110
	s_cmpk_lt_u32 s28, 0x75
	s_waitcnt lgkmcnt(1)
	v_mfma_f32_32x32x16_bf16 v[48:63], v[92:95], v[220:223], v[48:63]
	v_exp_f32_e32 v223, v104
	v_exp_f32_e32 v220, v108
	v_exp_f32_e32 v222, v109
	v_exp_f32_e32 v221, v111
	s_cbranch_scc1 .LBB0_352
; __device__ __forceinline__ void finishSM(f32x16& p0, f32x16& p1, float alpha, float& l_reg, bf16x8& pa0, bf16x8& pa1, bf16x8& pa2, bf16x8& pa3) {
;   for (int r = 0; r < 16; ++r) p1[r] = __builtin_amdgcn_exp2f(p1[r]);
;   float ps = 0; for (int r = 0; r < 16; ++r) ps += p0[r]; for (int r = 0; r < 16; ++r) ps += p1[r];
;   { auto rr = __builtin_amdgcn_permlane32_swap(__float_as_uint(ps), __float_as_uint(ps), false, false);
;     ps = __uint_as_float(rr[0]) + __uint_as_float(rr[1]); }
;   l_reg = l_reg * alpha + ps;
;     ...
;   PK4(p0, 0, pa0); PK4(p0, 8, pa1); PK4(p1, 0, pa2); PK4(p1, 8, pa3);
;     ...
; }
; __device__ __forceinline__ void qkt(f32x16& p0, f32x16& p1, const bf16* Ks, const bf16x8* qr, int r32, int hi) {
;   p0 = f32x16{}; p1 = f32x16{};
;   for (int d0 = 0; d0 < 8; ++d0) { int cb = (d0 * 16 + hi * 8) * 2;
;     bf16x8 b0 = *reinterpret_cast<const bf16x8*>((const char*)Ks + KSWZ(r32, cb));
;     bf16x8 b1 = *reinterpret_cast<const bf16x8*>((const char*)Ks + KSWZ(32 + r32, cb));
;     p0 = __builtin_amdgcn_mfma_f32_32x32x16_bf16(b0, qr[d0], p0, 0, 0, 0);
;     p1 = __builtin_amdgcn_mfma_f32_32x32x16_bf16(b1, qr[d0], p1, 0, 0, 0); }
; }
; __device__ __forceinline__ int v_st(int k, int c) { const int kk = (k & ~0xC) | ((k & 4) << 1) | ((k & 8) >> 1); return ((kk >> 3) * 4 + (c >> 5)) * 512 + ((kk & 7) * 32 + (c & 31)) * 2; }
; __device__ __forceinline__ int v_rd_base(int lane) { return ((lane & 3) << 3) | (((lane >> 2) & 3) << 6) | (((lane >> 4) & 1) << 5) | (((lane >> 5) & 1) << 8); }
; template <int OFF> __device__ __forceinline__ s16x4 tr_read(int vb) {
;   s16x4 r; asm volatile("ds_read_b64_tr_b16 %0, %1 offset:%2" : "=&v"(r) : "v"(vb), "i"(OFF) : "memory"); return r;
; }
; template <int D0> __device__ __forceinline__ void pv_one(f32x16& od, int vb, bf16x8 pa0, bf16x8 pa1, bf16x8 pa2, bf16x8 pa3) {
;   const s16x4 l0 = tr_read<v_rd_off(D0, 0, 0)>(vb), h0 = tr_read<v_rd_off(D0, 0, 1)>(vb), l1 = tr_read<v_rd_off(D0, 1, 0)>(vb), h1 = tr_read<v_rd_off(D0, 1, 1)>(vb);
;   const s16x4 l2 = tr_read<v_rd_off(D0, 2, 0)>(vb), h2 = tr_read<v_rd_off(D0, 2, 1)>(vb), l3 = tr_read<v_rd_off(D0, 3, 0)>(vb), h3 = tr_read<v_rd_off(D0, 3, 1)>(vb);
;   asm volatile("s_waitcnt lgkmcnt(0)" ::: "memory"); SBAR();
;     ...
;   od = __builtin_amdgcn_mfma_f32_32x32x16_bf16(pa0, PK(l0, h0), od, 0, 0, 0);
;   od = __builtin_amdgcn_mfma_f32_32x32x16_bf16(pa1, PK(l1, h1), od, 0, 0, 0);
	v_mov_b32_e32 v252, 0x7fc00000
	v_readlane_b32 s8, v255, 42
	v_readlane_b32 s9, v255, 43
	s_add_u32 s2, s8, s6
	s_addc_u32 s3, s9, s7
	s_lshl_b32 s4, s65, 1
	s_add_u32 s2, s2, s4
	s_addc_u32 s3, s3, 0
	v_ashrrev_i32_e32 v82, 1, v195
	v_mov_b64_e32 v[80:81], s[2:3]
	v_mad_i64_i32 v[80:81], s[2:3], v82, s17, v[80:81]
	v_lshlrev_b32_e32 v82, 7, v195
	v_and_b32_e32 v128, 0x80, v82
	v_lshl_add_u64 v[80:81], v[80:81], 0, v[128:129]
	s_add_u32 s4, s8, s64
	global_load_dword v216, v[80:81], off
	v_cmp_gt_i32_e32 vcc, s14, v195
	v_mov_b32_e32 v80, 0xa00
	v_mov_b32_e32 v81, 0x800
	s_addc_u32 s5, s9, s57
	v_cndmask_b32_e32 v80, v80, v81, vcc
	v_mov_b32_e32 v81, v129
	v_bfe_u32 v82, v195, 1, 7
	v_lshl_add_u64 v[80:81], s[4:5], 0, v[80:81]
	s_lshl_b32 s46, s56, 1
	v_mul_u32_u24_e32 v82, 0x600, v82
	v_lshl_add_u64 v[80:81], v[80:81], 0, s[46:47]
	v_lshlrev_b32_e32 v82, 1, v82
	v_mov_b32_e32 v83, v129
	v_lshl_add_u64 v[80:81], v[80:81], 0, v[82:83]
	v_lshl_add_u64 v[80:81], v[80:81], 0, v[128:129]
	global_load_dword v217, v[80:81], off
	v_and_b32_e32 v247, 0x3fffffc0, v195
	s_waitcnt lgkmcnt(0)
	s_barrier
	ds_read_b128 v[80:83], v207 offset:16384
	ds_read_b128 v[96:99], v207 offset:24576
	ds_read_b128 v[100:103], v208 offset:16384
	ds_read_b128 v[170:173], v208 offset:24576
	v_exp_f32_e32 v104, v68
	v_exp_f32_e32 v105, v69
	s_waitcnt lgkmcnt(3)
	v_mfma_f32_32x32x16_bf16 v[80:95], v[80:83], v[142:145], 0
	v_exp_f32_e32 v106, v70
	v_exp_f32_e32 v107, v71
	v_exp_f32_e32 v108, v72
	v_exp_f32_e32 v109, v73
	v_exp_f32_e32 v110, v74
	v_exp_f32_e32 v111, v75
	v_exp_f32_e32 v196, v76
	s_waitcnt lgkmcnt(1)
	v_mfma_f32_32x32x16_bf16 v[80:95], v[100:103], v[138:141], v[80:95]
	ds_read_b128 v[100:103], v209 offset:16384
	ds_read_b128 v[162:165], v209 offset:24576
	v_exp_f32_e32 v197, v77
	v_exp_f32_e32 v198, v78
	v_exp_f32_e32 v79, v79
	s_waitcnt lgkmcnt(1)
	v_mfma_f32_32x32x16_bf16 v[80:95], v[100:103], v[112:115], v[80:95]
	ds_read_b128 v[100:103], v210 offset:16384
	ds_read_b128 v[166:169], v210 offset:24576
	s_waitcnt lgkmcnt(1)
	v_mfma_f32_32x32x16_bf16 v[80:95], v[100:103], v[116:119], v[80:95]
	ds_read_b128 v[100:103], v190 offset:16384
	ds_read_b128 v[174:177], v190 offset:24576
	s_waitcnt lgkmcnt(1)
	v_mfma_f32_32x32x16_bf16 v[80:95], v[100:103], v[120:123], v[80:95]
	ds_read_b128 v[100:103], v191 offset:16384
	ds_read_b128 v[178:181], v191 offset:24576
	s_waitcnt lgkmcnt(1)
	v_mfma_f32_32x32x16_bf16 v[80:95], v[100:103], v[124:127], v[80:95]
	ds_read_b128 v[100:103], v192 offset:16384
	ds_read_b128 v[182:185], v192 offset:24576
	s_waitcnt lgkmcnt(1)
	v_mfma_f32_32x32x16_bf16 v[80:95], v[100:103], v[130:133], v[80:95]
	ds_read_b128 v[100:103], v193 offset:16384
	ds_read_b128 v[186:189], v193 offset:24576
	s_waitcnt lgkmcnt(1)
	v_mfma_f32_32x32x16_bf16 v[80:95], v[100:103], v[134:137], v[80:95]
	v_exp_f32_e32 v100, v64
	v_add_f32_e32 v64, 0, v229
	v_add_f32_e32 v64, v243, v64
	v_add_f32_e32 v64, v244, v64
	v_add_f32_e32 v64, v246, v64
	v_add_f32_e32 v64, v242, v64
	v_add_f32_e32 v64, v245, v64
	v_add_f32_e32 v64, v227, v64
	v_add_f32_e32 v64, v228, v64
	v_add_f32_e32 v64, v223, v64
	v_add_f32_e32 v64, v226, v64
	v_add_f32_e32 v64, v224, v64
	v_add_f32_e32 v64, v225, v64
	v_add_f32_e32 v64, v220, v64
	v_exp_f32_e32 v101, v65
	v_add_f32_e32 v64, v222, v64
	v_exp_f32_e32 v102, v66
	v_add_f32_e32 v64, v219, v64
	v_exp_f32_e32 v103, v67
	v_add_f32_e32 v64, v221, v64
	v_add_f32_e32 v64, v100, v64
	v_add_f32_e32 v64, v101, v64
	v_add_f32_e32 v64, v102, v64
	v_add_f32_e32 v64, v103, v64
	v_add_f32_e32 v64, v104, v64
	v_add_f32_e32 v64, v105, v64
	v_add_f32_e32 v64, v106, v64
	v_add_f32_e32 v64, v107, v64
	v_add_f32_e32 v64, v108, v64
	v_add_f32_e32 v64, v109, v64
	v_add_f32_e32 v64, v110, v64
	v_add_f32_e32 v64, v111, v64
	v_add_f32_e32 v64, v196, v64
	v_add_f32_e32 v64, v197, v64
	v_add_f32_e32 v64, v198, v64
	v_add_f32_e32 v128, v79, v64
	v_mov_b32_e32 v218, v128
	s_nop 1
	v_permlane32_swap_b32_e32 v128, v218
	v_cvt_pk_bf16_f32 v64, v229, v243
	v_cvt_pk_bf16_f32 v65, v244, v246
	v_cvt_pk_bf16_f32 v66, v242, v245
	v_cvt_pk_bf16_f32 v67, v227, v228
	v_cvt_pk_bf16_f32 v68, v223, v226
	v_cvt_pk_bf16_f32 v69, v224, v225
	v_cvt_pk_bf16_f32 v70, v220, v222
	v_cvt_pk_bf16_f32 v71, v219, v221
	v_cvt_pk_bf16_f32 v72, v100, v101
	v_cvt_pk_bf16_f32 v73, v102, v103
	v_cvt_pk_bf16_f32 v74, v104, v105
	v_cvt_pk_bf16_f32 v75, v106, v107
	v_cvt_pk_bf16_f32 v76, v108, v109
	v_cvt_pk_bf16_f32 v77, v110, v111
	v_cvt_pk_bf16_f32 v78, v196, v197
	v_cvt_pk_bf16_f32 v79, v198, v79
	s_nop 0
	v_permlane32_swap_b32_e32 v64, v66
	v_permlane32_swap_b32_e32 v65, v67
	v_permlane32_swap_b32_e32 v68, v70
	v_permlane32_swap_b32_e32 v69, v71
	v_permlane32_swap_b32_e32 v72, v74
	v_permlane32_swap_b32_e32 v73, v75
	v_permlane32_swap_b32_e32 v76, v78
	v_permlane32_swap_b32_e32 v77, v79
	ds_read_b64_tr_b16 v[100:101], v206 offset:0
	ds_read_b64_tr_b16 v[102:103], v206 offset:0x800
	ds_read_b64_tr_b16 v[104:105], v206 offset:0x1000
	ds_read_b64_tr_b16 v[106:107], v206 offset:0x1800
	ds_read_b64_tr_b16 v[108:109], v206 offset:0x2000
	ds_read_b64_tr_b16 v[110:111], v206 offset:0x2800
	ds_read_b64_tr_b16 v[220:221], v206 offset:0x3000
	ds_read_b64_tr_b16 v[222:223], v206 offset:0x3800
	s_waitcnt lgkmcnt(0)
	s_nop 0
	v_mfma_f32_32x32x16_bf16 v[0:15], v[64:67], v[100:103], v[0:15]
	ds_read_b64_tr_b16 v[100:101], v206 offset:0x200
	ds_read_b64_tr_b16 v[102:103], v206 offset:0xa00
	v_mfma_f32_32x32x16_bf16 v[0:15], v[68:71], v[104:107], v[0:15]
	ds_read_b64_tr_b16 v[104:105], v206 offset:0x1200
	ds_read_b64_tr_b16 v[106:107], v206 offset:0x1a00
	v_mfma_f32_32x32x16_bf16 v[0:15], v[72:75], v[108:111], v[0:15]
	ds_read_b64_tr_b16 v[108:109], v206 offset:0x2200
	ds_read_b64_tr_b16 v[110:111], v206 offset:0x2a00
	v_mfma_f32_32x32x16_bf16 v[0:15], v[76:79], v[220:223], v[0:15]
	ds_read_b64_tr_b16 v[220:221], v206 offset:0x3200
	ds_read_b64_tr_b16 v[222:223], v206 offset:0x3a00
	s_waitcnt lgkmcnt(0)
; __device__ __forceinline__ void finishSM(f32x16& p0, f32x16& p1, float alpha, float& l_reg, bf16x8& pa0, bf16x8& pa1, bf16x8& pa2, bf16x8& pa3) {
;   for (int r = 0; r < 16; ++r) p1[r] = __builtin_amdgcn_exp2f(p1[r]);
;   float ps = 0; for (int r = 0; r < 16; ++r) ps += p0[r]; for (int r = 0; r < 16; ++r) ps += p1[r];
;   { auto rr = __builtin_amdgcn_permlane32_swap(__float_as_uint(ps), __float_as_uint(ps), false, false);
;     ps = __uint_as_float(rr[0]) + __uint_as_float(rr[1]); }
;   l_reg = l_reg * alpha + ps;
;     ...
;   PK4(p0, 0, pa0); PK4(p0, 8, pa1); PK4(p1, 0, pa2); PK4(p1, 8, pa3);
;     ...
; }
; __device__ __forceinline__ void qkt(f32x16& p0, f32x16& p1, const bf16* Ks, const bf16x8* qr, int r32, int hi) {
;   p0 = f32x16{}; p1 = f32x16{};
;   for (int d0 = 0; d0 < 8; ++d0) { int cb = (d0 * 16 + hi * 8) * 2;
;     bf16x8 b0 = *reinterpret_cast<const bf16x8*>((const char*)Ks + KSWZ(r32, cb));
;     bf16x8 b1 = *reinterpret_cast<const bf16x8*>((const char*)Ks + KSWZ(32 + r32, cb));
;     p0 = __builtin_amdgcn_mfma_f32_32x32x16_bf16(b0, qr[d0], p0, 0, 0, 0);
;     p1 = __builtin_amdgcn_mfma_f32_32x32x16_bf16(b1, qr[d0], p1, 0, 0, 0); }
; }
; __device__ __forceinline__ int v_st(int k, int c) { const int kk = (k & ~0xC) | ((k & 4) << 1) | ((k & 8) >> 1); return ((kk >> 3) * 4 + (c >> 5)) * 512 + ((kk & 7) * 32 + (c & 31)) * 2; }
; __device__ __forceinline__ int v_rd_base(int lane) { return ((lane & 3) << 3) | (((lane >> 2) & 3) << 6) | (((lane >> 4) & 1) << 5) | (((lane >> 5) & 1) << 8); }
; template <int OFF> __device__ __forceinline__ s16x4 tr_read(int vb) {
;   s16x4 r; asm volatile("ds_read_b64_tr_b16 %0, %1 offset:%2" : "=&v"(r) : "v"(vb), "i"(OFF) : "memory"); return r;
; }
; template <int D0> __device__ __forceinline__ void pv_one(f32x16& od, int vb, bf16x8 pa0, bf16x8 pa1, bf16x8 pa2, bf16x8 pa3) {
;   const s16x4 l0 = tr_read<v_rd_off(D0, 0, 0)>(vb), h0 = tr_read<v_rd_off(D0, 0, 1)>(vb), l1 = tr_read<v_rd_off(D0, 1, 0)>(vb), h1 = tr_read<v_rd_off(D0, 1, 1)>(vb);
;   const s16x4 l2 = tr_read<v_rd_off(D0, 2, 0)>(vb), h2 = tr_read<v_rd_off(D0, 2, 1)>(vb), l3 = tr_read<v_rd_off(D0, 3, 0)>(vb), h3 = tr_read<v_rd_off(D0, 3, 1)>(vb);
;   asm volatile("s_waitcnt lgkmcnt(0)" ::: "memory"); SBAR();
;     ...
;   od = __builtin_amdgcn_mfma_f32_32x32x16_bf16(pa0, PK(l0, h0), od, 0, 0, 0);
;   od = __builtin_amdgcn_mfma_f32_32x32x16_bf16(pa1, PK(l1, h1), od, 0, 0, 0);
	v_mfma_f32_32x32x16_bf16 v[16:31], v[64:67], v[100:103], v[16:31]
	ds_read_b64_tr_b16 v[100:101], v206 offset:0x400
	ds_read_b64_tr_b16 v[102:103], v206 offset:0xc00
	v_mfma_f32_32x32x16_bf16 v[16:31], v[68:71], v[104:107], v[16:31]
	ds_read_b64_tr_b16 v[104:105], v206 offset:0x1400
	ds_read_b64_tr_b16 v[106:107], v206 offset:0x1c00
	v_mfma_f32_32x32x16_bf16 v[16:31], v[72:75], v[108:111], v[16:31]
	ds_read_b64_tr_b16 v[108:109], v206 offset:0x2400
	ds_read_b64_tr_b16 v[110:111], v206 offset:0x2c00
	v_mfma_f32_32x32x16_bf16 v[16:31], v[76:79], v[220:223], v[16:31]
	ds_read_b64_tr_b16 v[220:221], v206 offset:0x3400
	ds_read_b64_tr_b16 v[222:223], v206 offset:0x3c00
	s_waitcnt lgkmcnt(0)
	v_mfma_f32_32x32x16_bf16 v[32:47], v[64:67], v[100:103], v[32:47]
	ds_read_b64_tr_b16 v[100:101], v206 offset:0x600
	ds_read_b64_tr_b16 v[102:103], v206 offset:0xe00
	v_mfma_f32_32x32x16_bf16 v[32:47], v[68:71], v[104:107], v[32:47]
	ds_read_b64_tr_b16 v[104:105], v206 offset:0x1600
	ds_read_b64_tr_b16 v[106:107], v206 offset:0x1e00
	v_mfma_f32_32x32x16_bf16 v[32:47], v[72:75], v[108:111], v[32:47]
	ds_read_b64_tr_b16 v[108:109], v206 offset:0x2600
	ds_read_b64_tr_b16 v[110:111], v206 offset:0x2e00
	v_mfma_f32_32x32x16_bf16 v[32:47], v[76:79], v[220:223], v[32:47]
	ds_read_b64_tr_b16 v[220:221], v206 offset:0x3600
	ds_read_b64_tr_b16 v[222:223], v206 offset:0x3e00
	s_waitcnt lgkmcnt(0)
	v_mfma_f32_32x32x16_bf16 v[48:63], v[64:67], v[100:103], v[48:63]
	s_waitcnt vmcnt(5)
	ds_write_b128 v211, v[146:149] offset:32768
	s_waitcnt vmcnt(3)
	ds_write_b128 v212, v[150:153] offset:32768
	ds_write_b128 v213, v[154:157] offset:32768
	s_waitcnt vmcnt(2)
	ds_write_b128 v214, v[158:161] offset:32768
	s_waitcnt lgkmcnt(0)
	s_barrier
	v_mfma_f32_32x32x16_bf16 v[48:63], v[68:71], v[104:107], v[48:63]
	v_mfma_f32_32x32x16_bf16 v[48:63], v[72:75], v[108:111], v[48:63]
	v_mfma_f32_32x32x16_bf16 v[48:63], v[76:79], v[220:223], v[48:63]
	ds_read_b128 v[64:67], v207 offset:32768
	ds_read_b128 v[100:103], v208 offset:32768
	s_add_i32 s2, 0, 0x18000
	s_waitcnt lgkmcnt(1)
	v_mfma_f32_32x32x16_bf16 v[64:79], v[64:67], v[142:145], 0
	s_waitcnt lgkmcnt(0)
	v_mfma_f32_32x32x16_bf16 v[64:79], v[100:103], v[138:141], v[64:79]
	ds_read_b128 v[100:103], v209 offset:32768
	s_waitcnt lgkmcnt(0)
	v_mfma_f32_32x32x16_bf16 v[64:79], v[100:103], v[112:115], v[64:79]
	ds_read_b128 v[100:103], v210 offset:32768
	s_waitcnt lgkmcnt(0)
	v_mfma_f32_32x32x16_bf16 v[64:79], v[100:103], v[116:119], v[64:79]
	ds_read_b128 v[100:103], v190 offset:32768
	s_waitcnt lgkmcnt(0)
	v_mfma_f32_32x32x16_bf16 v[64:79], v[100:103], v[120:123], v[64:79]
	ds_read_b128 v[100:103], v191 offset:32768
	s_waitcnt lgkmcnt(0)
	v_mfma_f32_32x32x16_bf16 v[64:79], v[100:103], v[124:127], v[64:79]
	ds_read_b128 v[100:103], v192 offset:32768
	s_waitcnt lgkmcnt(0)
	v_mfma_f32_32x32x16_bf16 v[64:79], v[100:103], v[130:133], v[64:79]
	ds_read_b128 v[100:103], v193 offset:32768
	s_waitcnt lgkmcnt(0)
	v_and_b32_e32 v190, 63, v195
	v_lshlrev_b32_e32 v191, 4, v195
	v_and_b32_e32 v192, 31, v195
	v_bfe_u32 v193, v195, 5, 1
	v_mfma_f32_32x32x16_bf16 v[64:79], v[100:103], v[134:137], v[64:79]
	v_mfma_f32_32x32x16_bf16 v[96:111], v[96:99], v[142:145], 0
	s_nop 10
	v_exp_f32_e32 v72, v80
	v_exp_f32_e32 v80, v81
	v_exp_f32_e32 v73, v82
	v_exp_f32_e32 v81, v83
	v_exp_f32_e32 v74, v84
	v_add_f32_e32 v84, 0, v72
	v_exp_f32_e32 v82, v85
	v_mfma_f32_32x32x16_bf16 v[96:111], v[170:173], v[138:141], v[96:111]
	v_add_f32_e32 v84, v80, v84
	v_exp_f32_e32 v75, v86
	v_add_f32_e32 v84, v73, v84
	v_exp_f32_e32 v83, v87
	v_add_f32_e32 v84, v81, v84
	v_exp_f32_e32 v76, v88
	v_add_f32_e32 v84, v74, v84
	v_mfma_f32_32x32x16_bf16 v[96:111], v[162:165], v[112:115], v[96:111]
	v_exp_f32_e32 v85, v89
	v_add_f32_e32 v84, v82, v84
	v_exp_f32_e32 v77, v90
	v_add_f32_e32 v84, v75, v84
	v_exp_f32_e32 v87, v91
	v_add_f32_e32 v84, v83, v84
	v_exp_f32_e32 v78, v92
	v_mfma_f32_32x32x16_bf16 v[96:111], v[166:169], v[116:119], v[96:111]
	v_add_f32_e32 v84, v76, v84
	v_exp_f32_e32 v89, v93
	v_add_f32_e32 v84, v85, v84
	v_exp_f32_e32 v79, v94
	v_add_f32_e32 v84, v77, v84
	v_exp_f32_e32 v90, v95
	v_add_f32_e32 v84, v87, v84
	v_mfma_f32_32x32x16_bf16 v[96:111], v[174:177], v[120:123], v[96:111]
	v_add_f32_e32 v84, v78, v84
	v_add_f32_e32 v84, v89, v84
	v_add_f32_e32 v84, v79, v84
	v_add_f32_e32 v84, v90, v84
	v_lshl_add_u32 v88, v247, 2, s2
	v_cvt_pk_bf16_f32 v72, v72, v80
	v_cvt_pk_bf16_f32 v73, v73, v81
	v_mfma_f32_32x32x16_bf16 v[96:111], v[178:181], v[124:127], v[96:111]
	v_cvt_pk_bf16_f32 v74, v74, v82
	v_cvt_pk_bf16_f32 v75, v75, v83
	v_cvt_pk_bf16_f32 v76, v76, v85
	v_cvt_pk_bf16_f32 v77, v77, v87
	v_cvt_pk_bf16_f32 v78, v78, v89
	v_cvt_pk_bf16_f32 v79, v79, v90
	s_nop 0
	v_permlane32_swap_b32_e32 v72, v74
	v_mfma_f32_32x32x16_bf16 v[96:111], v[182:185], v[130:133], v[96:111]
	v_permlane32_swap_b32_e32 v73, v75
	v_permlane32_swap_b32_e32 v76, v78
	v_permlane32_swap_b32_e32 v77, v79
	v_mfma_f32_32x32x16_bf16 v[96:111], v[186:189], v[134:137], v[96:111]
	s_nop 11
	v_exp_f32_e32 v91, v96
	v_exp_f32_e32 v92, v97
	v_exp_f32_e32 v93, v98
	v_exp_f32_e32 v94, v99
	v_exp_f32_e32 v95, v100
	v_add_f32_e32 v84, v84, v91
	v_exp_f32_e32 v96, v101
	v_add_f32_e32 v84, v92, v84
	v_exp_f32_e32 v97, v102
	v_add_f32_e32 v84, v93, v84
	v_exp_f32_e32 v98, v103
	v_add_f32_e32 v84, v94, v84
	v_exp_f32_e32 v99, v104
	v_add_f32_e32 v84, v95, v84
	v_exp_f32_e32 v100, v105
	v_add_f32_e32 v84, v96, v84
	v_exp_f32_e32 v101, v106
	v_add_f32_e32 v84, v97, v84
	v_exp_f32_e32 v102, v107
	v_add_f32_e32 v84, v98, v84
	v_exp_f32_e32 v103, v108
	v_add_f32_e32 v84, v99, v84
	v_exp_f32_e32 v104, v109
	v_add_f32_e32 v84, v100, v84
	v_exp_f32_e32 v105, v110
	v_add_f32_e32 v84, v101, v84
	v_exp_f32_e32 v106, v111
	v_add_f32_e32 v84, v102, v84
	v_add_f32_e32 v84, v103, v84
	v_add_f32_e32 v84, v104, v84
	v_add_f32_e32 v84, v105, v84
	v_add_f32_e32 v84, v106, v84
	v_mov_b32_e32 v86, v84
	s_nop 1
	v_permlane32_swap_b32_e32 v84, v86
	v_cvt_pk_bf16_f32 v80, v91, v92
	v_cvt_pk_bf16_f32 v81, v93, v94
	v_cvt_pk_bf16_f32 v82, v95, v96
	v_cvt_pk_bf16_f32 v83, v97, v98
	v_cvt_pk_bf16_f32 v90, v99, v100
	v_cvt_pk_bf16_f32 v91, v101, v102
	v_cvt_pk_bf16_f32 v92, v103, v104
	v_cvt_pk_bf16_f32 v93, v105, v106
	s_nop 0
	v_permlane32_swap_b32_e32 v80, v82
	v_permlane32_swap_b32_e32 v81, v83
	v_permlane32_swap_b32_e32 v90, v92
	v_permlane32_swap_b32_e32 v91, v93
	ds_read_b64_tr_b16 v[94:95], v206 offset:0x4000
	ds_read_b64_tr_b16 v[96:97], v206 offset:0x4800
	ds_read_b64_tr_b16 v[98:99], v206 offset:0x5000
	ds_read_b64_tr_b16 v[100:101], v206 offset:0x5800
	ds_read_b64_tr_b16 v[102:103], v206 offset:0x6000
	ds_read_b64_tr_b16 v[104:105], v206 offset:0x6800
	ds_read_b64_tr_b16 v[106:107], v206 offset:0x7000
	ds_read_b64_tr_b16 v[108:109], v206 offset:0x7800
	s_waitcnt lgkmcnt(0)
; template <int D0> __device__ __forceinline__ void pv_one(f32x16& od, int vb, bf16x8 pa0, bf16x8 pa1, bf16x8 pa2, bf16x8 pa3) {
;   const s16x4 l0 = tr_read<v_rd_off(D0, 0, 0)>(vb), h0 = tr_read<v_rd_off(D0, 0, 1)>(vb), l1 = tr_read<v_rd_off(D0, 1, 0)>(vb), h1 = tr_read<v_rd_off(D0, 1, 1)>(vb);
;   const s16x4 l2 = tr_read<v_rd_off(D0, 2, 0)>(vb), h2 = tr_read<v_rd_off(D0, 2, 1)>(vb), l3 = tr_read<v_rd_off(D0, 3, 0)>(vb), h3 = tr_read<v_rd_off(D0, 3, 1)>(vb);
;   asm volatile("s_waitcnt lgkmcnt(0)" ::: "memory"); SBAR();
;     ...
;   od = __builtin_amdgcn_mfma_f32_32x32x16_bf16(pa0, PK(l0, h0), od, 0, 0, 0);
;   od = __builtin_amdgcn_mfma_f32_32x32x16_bf16(pa1, PK(l1, h1), od, 0, 0, 0);
;   od = __builtin_amdgcn_mfma_f32_32x32x16_bf16(pa2, PK(l2, h2), od, 0, 0, 0);
;   od = __builtin_amdgcn_mfma_f32_32x32x16_bf16(pa3, PK(l3, h3), od, 0, 0, 0);
;     ...
; }
; __device__ __forceinline__ void pv_d0(f32x16* o, int vb, bf16x8 pa0, bf16x8 pa1, bf16x8 pa2, bf16x8 pa3) {
;   pv_one<0>(o[0], vb, pa0, pa1, pa2, pa3); pv_one<1>(o[1], vb, pa0, pa1, pa2, pa3); pv_one<2>(o[2], vb, pa0, pa1, pa2, pa3); pv_one<3>(o[3], vb, pa0, pa1, pa2, pa3);
; }
; template <int BOFF> __device__ __forceinline__ void qkt_i(f32x16& p0, f32x16& p1, const int (&kb)[4], const bf16x8* qr) {
;   p0 = f32x16{}; p1 = f32x16{};
; #pragma unroll
;   for (int d0 = 0; d0 < 8; ++d0) { const int off = BOFF + (d0 >> 2) * 128;
;     const bf16x8 b0 = LDSV(kb[d0 & 3] + off), b1 = LDSV(kb[d0 & 3] + off + 8192);
;     p0 = __builtin_amdgcn_mfma_f32_32x32x16_bf16(b0, qr[d0], p0, 0, 0, 0);
;     p1 = __builtin_amdgcn_mfma_f32_32x32x16_bf16(b1, qr[d0], p1, 0, 0, 0); }
; }
; template <int D0, int BOFF> __device__ __forceinline__ void pv_one_i(f32x16& od, int vb, bf16x8 pa0, bf16x8 pa1, bf16x8 pa2, bf16x8 pa3) {
;   const s16x4 l0 = tr_read<BOFF + v_rd_off(D0, 0, 0)>(vb), h0 = tr_read<BOFF + v_rd_off(D0, 0, 1)>(vb), l1 = tr_read<BOFF + v_rd_off(D0, 1, 0)>(vb), h1 = tr_read<BOFF + v_rd_off(D0, 1, 1)>(vb);
;   const s16x4 l2 = tr_read<BOFF + v_rd_off(D0, 2, 0)>(vb), h2 = tr_read<BOFF + v_rd_off(D0, 2, 1)>(vb), l3 = tr_read<BOFF + v_rd_off(D0, 3, 0)>(vb), h3 = tr_read<BOFF + v_rd_off(D0, 3, 1)>(vb);
;   asm volatile("s_waitcnt lgkmcnt(0)" ::: "memory"); SBAR();
;     ...
;   od = __builtin_amdgcn_mfma_f32_32x32x16_bf16(pa0, PK(l0, h0), od, 0, 0, 0);
;   od = __builtin_amdgcn_mfma_f32_32x32x16_bf16(pa1, PK(l1, h1), od, 0, 0, 0);
	s_nop 0
	v_mfma_f32_32x32x16_bf16 v[0:15], v[72:75], v[94:97], v[0:15]
	ds_read_b64_tr_b16 v[94:95], v206 offset:0x4200
	ds_read_b64_tr_b16 v[96:97], v206 offset:0x4a00
	v_mfma_f32_32x32x16_bf16 v[0:15], v[76:79], v[98:101], v[0:15]
	ds_read_b64_tr_b16 v[98:99], v206 offset:0x5200
	ds_read_b64_tr_b16 v[100:101], v206 offset:0x5a00
	v_mfma_f32_32x32x16_bf16 v[0:15], v[80:83], v[102:105], v[0:15]
	ds_read_b64_tr_b16 v[102:103], v206 offset:0x6200
	ds_read_b64_tr_b16 v[104:105], v206 offset:0x6a00
	v_mfma_f32_32x32x16_bf16 v[0:15], v[90:93], v[106:109], v[0:15]
	ds_read_b64_tr_b16 v[106:107], v206 offset:0x7200
	ds_read_b64_tr_b16 v[108:109], v206 offset:0x7a00
	s_waitcnt lgkmcnt(0)
	v_mfma_f32_32x32x16_bf16 v[16:31], v[72:75], v[94:97], v[16:31]
	ds_read_b64_tr_b16 v[94:95], v206 offset:0x4400
	ds_read_b64_tr_b16 v[96:97], v206 offset:0x4c00
	v_mfma_f32_32x32x16_bf16 v[16:31], v[76:79], v[98:101], v[16:31]
	ds_read_b64_tr_b16 v[98:99], v206 offset:0x5400
	ds_read_b64_tr_b16 v[100:101], v206 offset:0x5c00
	v_mfma_f32_32x32x16_bf16 v[16:31], v[80:83], v[102:105], v[16:31]
	ds_read_b64_tr_b16 v[102:103], v206 offset:0x6400
	ds_read_b64_tr_b16 v[104:105], v206 offset:0x6c00
	v_mfma_f32_32x32x16_bf16 v[16:31], v[90:93], v[106:109], v[16:31]
	ds_read_b64_tr_b16 v[106:107], v206 offset:0x7400
	ds_read_b64_tr_b16 v[108:109], v206 offset:0x7c00
	s_waitcnt lgkmcnt(0)
	v_mfma_f32_32x32x16_bf16 v[32:47], v[72:75], v[94:97], v[32:47]
	ds_read_b64_tr_b16 v[94:95], v206 offset:0x4600
	ds_read_b64_tr_b16 v[96:97], v206 offset:0x4e00
	v_mfma_f32_32x32x16_bf16 v[32:47], v[76:79], v[98:101], v[32:47]
	ds_read_b64_tr_b16 v[98:99], v206 offset:0x5600
	ds_read_b64_tr_b16 v[100:101], v206 offset:0x5e00
	v_mfma_f32_32x32x16_bf16 v[32:47], v[80:83], v[102:105], v[32:47]
	ds_read_b64_tr_b16 v[102:103], v206 offset:0x6600
	ds_read_b64_tr_b16 v[104:105], v206 offset:0x6e00
	v_mfma_f32_32x32x16_bf16 v[32:47], v[90:93], v[106:109], v[32:47]
	ds_read_b64_tr_b16 v[106:107], v206 offset:0x7600
	ds_read_b64_tr_b16 v[108:109], v206 offset:0x7e00
	s_waitcnt lgkmcnt(0)
	v_mfma_f32_32x32x16_bf16 v[48:63], v[72:75], v[94:97], v[48:63]
	v_exp_f32_e32 v64, v64
	v_exp_f32_e32 v65, v65
	v_exp_f32_e32 v66, v66
	v_exp_f32_e32 v67, v67
	v_exp_f32_e32 v68, v68
	v_exp_f32_e32 v69, v69
	v_exp_f32_e32 v70, v70
	v_mfma_f32_32x32x16_bf16 v[48:63], v[76:79], v[98:101], v[48:63]
	v_exp_f32_e32 v71, v71
	v_mfma_f32_32x32x16_bf16 v[48:63], v[80:83], v[102:105], v[48:63]
	v_mfma_f32_32x32x16_bf16 v[48:63], v[90:93], v[106:109], v[48:63]
	v_add_f32_e32 v72, 0, v64
	v_add_f32_e32 v72, v65, v72
	v_add_f32_e32 v72, v66, v72
	v_add_f32_e32 v72, v67, v72
	v_add_f32_e32 v72, v68, v72
	v_add_f32_e32 v72, v69, v72
	v_add_f32_e32 v72, v70, v72
	v_add_f32_e32 v72, v71, v72
	v_add_f32_e32 v85, 0, v72
	v_mov_b32_e32 v87, v85
	s_nop 1
	v_permlane32_swap_b32_e32 v85, v87
	v_cvt_pk_bf16_f32 v64, v64, v65
	v_cvt_pk_bf16_f32 v65, v66, v67
	v_cvt_pk_bf16_f32 v66, v68, v69
	v_cvt_pk_bf16_f32 v67, v70, v71
	v_cvt_pk_bf16_f32 v68, v129, v129
	v_cvt_pk_bf16_f32 v69, v129, v129
	v_cvt_pk_bf16_f32 v70, v129, v129
	v_cvt_pk_bf16_f32 v71, v129, v129
	v_cvt_pk_bf16_f32 v72, v129, v129
	v_cvt_pk_bf16_f32 v73, v129, v129
	v_cvt_pk_bf16_f32 v74, v129, v129
	v_cvt_pk_bf16_f32 v75, v129, v129
	v_cvt_pk_bf16_f32 v76, v129, v129
	v_cvt_pk_bf16_f32 v77, v129, v129
	v_cvt_pk_bf16_f32 v78, v129, v129
	v_cvt_pk_bf16_f32 v79, v129, v129
	s_nop 0
	v_permlane32_swap_b32_e32 v64, v66
	v_permlane32_swap_b32_e32 v65, v67
	v_permlane32_swap_b32_e32 v68, v70
	v_permlane32_swap_b32_e32 v69, v71
	v_permlane32_swap_b32_e32 v72, v74
	v_permlane32_swap_b32_e32 v73, v75
	v_permlane32_swap_b32_e32 v76, v78
	v_permlane32_swap_b32_e32 v77, v79
	ds_read_b64_tr_b16 v[80:81], v206 offset:0x8000
	ds_read_b64_tr_b16 v[82:83], v206 offset:0x8800
	ds_read_b64_tr_b16 v[90:91], v206 offset:0x9000
	ds_read_b64_tr_b16 v[92:93], v206 offset:0x9800
	ds_read_b64_tr_b16 v[94:95], v206 offset:0xa000
	ds_read_b64_tr_b16 v[96:97], v206 offset:0xa800
	ds_read_b64_tr_b16 v[98:99], v206 offset:0xb000
	ds_read_b64_tr_b16 v[100:101], v206 offset:0xb800
	s_waitcnt lgkmcnt(0)
	s_nop 0
	v_mfma_f32_32x32x16_bf16 v[0:15], v[64:67], v[80:83], v[0:15]
	ds_read_b64_tr_b16 v[80:81], v206 offset:0x8200
	ds_read_b64_tr_b16 v[82:83], v206 offset:0x8a00
	v_mfma_f32_32x32x16_bf16 v[0:15], v[68:71], v[90:93], v[0:15]
	ds_read_b64_tr_b16 v[90:91], v206 offset:0x9200
	ds_read_b64_tr_b16 v[92:93], v206 offset:0x9a00
	v_mfma_f32_32x32x16_bf16 v[0:15], v[72:75], v[94:97], v[0:15]
	ds_read_b64_tr_b16 v[94:95], v206 offset:0xa200
	ds_read_b64_tr_b16 v[96:97], v206 offset:0xaa00
	v_mfma_f32_32x32x16_bf16 v[0:15], v[76:79], v[98:101], v[0:15]
	ds_read_b64_tr_b16 v[98:99], v206 offset:0xb200
	ds_read_b64_tr_b16 v[100:101], v206 offset:0xba00
	s_waitcnt lgkmcnt(0)
	v_mfma_f32_32x32x16_bf16 v[16:31], v[64:67], v[80:83], v[16:31]
	ds_read_b64_tr_b16 v[80:81], v206 offset:0x8400
	ds_read_b64_tr_b16 v[82:83], v206 offset:0x8c00
	v_mfma_f32_32x32x16_bf16 v[16:31], v[68:71], v[90:93], v[16:31]
	ds_read_b64_tr_b16 v[90:91], v206 offset:0x9400
	ds_read_b64_tr_b16 v[92:93], v206 offset:0x9c00
	v_mfma_f32_32x32x16_bf16 v[16:31], v[72:75], v[94:97], v[16:31]
	ds_read_b64_tr_b16 v[94:95], v206 offset:0xa400
	ds_read_b64_tr_b16 v[96:97], v206 offset:0xac00
	v_mfma_f32_32x32x16_bf16 v[16:31], v[76:79], v[98:101], v[16:31]
	ds_read_b64_tr_b16 v[98:99], v206 offset:0xb400
	ds_read_b64_tr_b16 v[100:101], v206 offset:0xbc00
	s_waitcnt lgkmcnt(0)
	v_mfma_f32_32x32x16_bf16 v[32:47], v[64:67], v[80:83], v[32:47]
	ds_read_b64_tr_b16 v[80:81], v206 offset:0x8600
	ds_read_b64_tr_b16 v[82:83], v206 offset:0x8e00
	v_mfma_f32_32x32x16_bf16 v[32:47], v[68:71], v[90:93], v[32:47]
	ds_read_b64_tr_b16 v[90:91], v206 offset:0x9600
	ds_read_b64_tr_b16 v[92:93], v206 offset:0x9e00
	v_mfma_f32_32x32x16_bf16 v[32:47], v[72:75], v[94:97], v[32:47]
	ds_read_b64_tr_b16 v[94:95], v206 offset:0xa600
	ds_read_b64_tr_b16 v[96:97], v206 offset:0xae00
	v_mfma_f32_32x32x16_bf16 v[32:47], v[76:79], v[98:101], v[32:47]
	ds_read_b64_tr_b16 v[98:99], v206 offset:0xb600
	ds_read_b64_tr_b16 v[100:101], v206 offset:0xbe00
	s_waitcnt lgkmcnt(0)
	v_mfma_f32_32x32x16_bf16 v[48:63], v[64:67], v[80:83], v[48:63]
	v_cmp_gt_u32_e32 vcc, 32, v190
	v_mfma_f32_32x32x16_bf16 v[48:63], v[68:71], v[90:93], v[48:63]
	v_mfma_f32_32x32x16_bf16 v[48:63], v[72:75], v[94:97], v[48:63]
	v_mfma_f32_32x32x16_bf16 v[48:63], v[76:79], v[98:101], v[48:63]
	s_and_saveexec_b64 s[28:29], vcc
	s_cbranch_execz .LBB0_309
	v_add_f32_e32 v64, v128, v218
	v_add_f32_e32 v66, v215, v64
	v_pk_add_f32 v[64:65], v[84:85], v[86:87]
	v_lshl_add_u32 v67, v192, 2, v88
	v_add_f32_e32 v64, v66, v64
	v_add_f32_e32 v64, v64, v65
	ds_write_b32 v67, v64
	s_branch .LBB0_309
